# last layer: one fused 16-row resid2 pass per wave ordered so that each wave consumes the FH1 rows lying under its own f32 output rows first; the grid barrier between the token halves is no longer exec
# speedup vs baseline: 1.0057x; 1.0057x over previous
; __device__ __forceinline__ float bflo(unsigned w) { return __uint_as_float(w << 16); }
; __device__ __forceinline__ float bfhi(unsigned w) { return __uint_as_float(w & 0xffff0000u); }
; __device__ __forceinline__ void resid_rows(bf16_t* R, const bf16_t* Y, const float* ssqY, const float* g, float* rstd_out, float* outf, bool wf32, int row_lo, int row_hi, int yoff, int gw, int NGW, int lane) {
;     ...
;         for (int k = 0; k < RP; ++k) { const int row = row0 + k * NGW; const bool ok = row < row_hi; const int rw = ok ? row : row0;
;             ssv[k] = ssqY[rw];
; #pragma unroll
;             for (int j = 0; j < 2; ++j) { const int c = 8 * lane + 512 * j; rr[k][j] = *(const u32x4*)(R + (size_t)rw * DM + c); oo[k][j] = *(const u32x4*)(Y + (size_t)(rw - yoff) * DM + c); } }
; #pragma unroll
;         for (int k = 0; k < RP; ++k) { const int row = row0 + k * NGW; if (row < row_hi) {
;             const float rs = __builtin_amdgcn_rsqf(ssv[k] * (1.0f / DM) + RMS_EPS); float s = 0.f;
; #pragma unroll
;             for (int j = 0; j < 2; ++j) { const int c = 8 * lane + 512 * j; const u32x4 r = rr[k][j], o = oo[k][j]; const f32x4 ga = gv[j][0], gb = gv[j][1];
;                 f32x4 ya, yb; ya[0] = bflo(r.x) + bflo(o.x) * rs * ga[0]; ya[1] = bfhi(r.x) + bfhi(o.x) * rs * ga[1]; ya[2] = bflo(r.y) + bflo(o.y) * rs * ga[2]; ya[3] = bfhi(r.y) + bfhi(o.y) * rs * ga[3];
;                 yb[0] = bflo(r.z) + bflo(o.z) * rs * gb[0]; yb[1] = bfhi(r.z) + bfhi(o.z) * rs * gb[1]; yb[2] = bflo(r.w) + bflo(o.w) * rs * gb[2]; yb[3] = bfhi(r.w) + bfhi(o.w) * rs * gb[3];
;                 if (wf32) { *(f32x4*)(outf + (size_t)row * DM + c) = ya; *(f32x4*)(outf + (size_t)row * DM + c + 4) = yb; }
;                 s += (ya[0] * ya[0] + ya[1] * ya[1]) + (ya[2] * ya[2] + ya[3] * ya[3]) + (yb[0] * yb[0] + yb[1] * yb[1]) + (yb[2] * yb[2] + yb[3] * yb[3]);
;                 u32x4 w; w.x = pk2(ya[0], ya[1]); w.y = pk2(ya[2], ya[3]); w.z = pk2(yb[0], yb[1]); w.w = pk2(yb[2], yb[3]); *(u32x4*)(R + (size_t)row * DM + c) = w; }
; __global__ void __launch_bounds__(512, 2) fwd_megakernel(Params P) {
;     ...
;         if (EN(7) && IN(pb + 8)) {
;             const bool lastl = (l == NLAYER - 1);
;             { const int lane = otid() & 63, gw = bx * 8 + (otid() >> 6);
;               resid_rows(XB, FH1, ssqF, PIN(I_LNFPOST) + l * DM, rstdA, out, lastl, HALF_TOK, MTOK, HALF_TOK, gw, NGW, lane); }
.Lrs2_last1:
	v_lshrrev_b32_e32 v114, 6, v0
	v_readlane_b32 s12, v255, 49
	v_readlane_b32 s13, v255, 4
	v_readfirstlane_b32 s18, v114
	s_load_dwordx2 s[4:5], s[0:1], 0x98
	s_load_dwordx2 s[10:11], s[0:1], 0x68
	s_load_dwordx2 s[6:7], s[0:1], 0x90
	s_add_i32 s13, s13, s18
	v_and_b32_e32 v115, 63, v0
	v_lshlrev_b32_e32 v114, 4, v115
	v_lshlrev_b32_e32 v115, 5, v115
	s_lshl_b32 s18, s12, 12
	s_lshl_b32 s19, s12, 18
	s_bfm_b64 s[8:9], 1, 63
	s_waitcnt lgkmcnt(0)
	s_add_u32 s10, s10, s18
	s_addc_u32 s11, s11, 0
	global_load_dwordx4 v[2:5], v115, s[10:11] offset:2048
	global_load_dwordx4 v[6:9], v115, s[10:11] offset:2064
	global_load_dwordx4 v[10:13], v115, s[10:11]
	global_load_dwordx4 v[14:17], v115, s[10:11] offset:16
	s_lshl_b32 s18, s13, 11
	v_add_u32_e32 v18, s18, v114
	v_mov_b32_e32 v19, v18
	v_mov_b32_e32 v20, v18
	s_lshl_b32 s18, s13, 2
	v_mov_b32_e32 v22, s18
	s_add_i32 s18, s18, s19
	v_mov_b32_e32 v21, s18
	s_lshl_b32 s18, s13, 12
	v_add_u32_e32 v23, s18, v115
	v_add_u32_e32 v18, 0x5001000, v18
	s_lshl_b32 s18, s13, 11
	v_add_u32_e32 v18, s18, v18
	s_lshl_b32 s18, s13, 11
	v_add_u32_e32 v20, s18, v20
	v_add_u32_e32 v21, 0x2d70000, v21
	s_lshl_b32 s18, s13, 2
	v_add_u32_e32 v21, s18, v21
	global_load_dwordx4 v[24:27], v18, s[4:5]
	global_load_dwordx4 v[32:35], v20, s[6:7]
	global_load_dwordx4 v[28:31], v18, s[4:5] offset:1024
	global_load_dwordx4 v[36:39], v20, s[6:7] offset:1024
	global_load_dword v40, v21, s[4:5]
	v_add_u32_e32 v18, 0x800, v18
	v_add_u32_e32 v20, 0x800, v20
	v_add_u32_e32 v21, 0x4, v21
	global_load_dwordx4 v[42:45], v18, s[4:5]
	global_load_dwordx4 v[50:53], v20, s[6:7]
	global_load_dwordx4 v[46:49], v18, s[4:5] offset:1024
	global_load_dwordx4 v[54:57], v20, s[6:7] offset:1024
	global_load_dword v58, v21, s[4:5]
	v_add_u32_e32 v18, 0x7ff800, v18
	v_add_u32_e32 v20, 0x7ff800, v20
	v_add_u32_e32 v21, 0x3ffc, v21
	global_load_dwordx4 v[60:63], v18, s[4:5]
	global_load_dwordx4 v[68:71], v20, s[6:7]
	global_load_dwordx4 v[64:67], v18, s[4:5] offset:1024
	global_load_dwordx4 v[72:75], v20, s[6:7] offset:1024
	global_load_dword v76, v21, s[4:5]
	v_add_u32_e32 v18, 0x800, v18
	v_add_u32_e32 v20, 0x800, v20
	v_add_u32_e32 v21, 0x4, v21
	global_load_dwordx4 v[78:81], v18, s[4:5]
	global_load_dwordx4 v[86:89], v20, s[6:7]
	global_load_dwordx4 v[82:85], v18, s[4:5] offset:1024
	global_load_dwordx4 v[90:93], v20, s[6:7] offset:1024
	global_load_dword v94, v21, s[4:5]
	s_waitcnt vmcnt(15)
	v_fmamk_f32 v96, v40, 0x3a800000, v244
	v_rsq_f32_e32 v96, v96
	v_add_u32_e32 v23, 0x4000000, v23
	s_lshl_b32 s18, s13, 12
	v_add_u32_e32 v23, s18, v23
	v_lshlrev_b32_e32 v106, 16, v32
	v_and_b32_e32 v107, 0xffff0000, v32
	v_lshlrev_b32_e32 v108, 16, v24
	v_and_b32_e32 v109, 0xffff0000, v24
	v_pk_mul_f32 v[106:107], v[96:97], v[106:107] op_sel_hi:[0,1]
	v_pk_fma_f32 v[98:99], v[10:11], v[106:107], v[108:109]
	v_lshlrev_b32_e32 v106, 16, v33
	v_and_b32_e32 v107, 0xffff0000, v33
	v_lshlrev_b32_e32 v108, 16, v25
	v_and_b32_e32 v109, 0xffff0000, v25
	v_pk_mul_f32 v[106:107], v[96:97], v[106:107] op_sel_hi:[0,1]
	v_pk_fma_f32 v[100:101], v[12:13], v[106:107], v[108:109]
	v_lshlrev_b32_e32 v106, 16, v34
	v_and_b32_e32 v107, 0xffff0000, v34
	v_lshlrev_b32_e32 v108, 16, v26
	v_and_b32_e32 v109, 0xffff0000, v26
	v_pk_mul_f32 v[106:107], v[96:97], v[106:107] op_sel_hi:[0,1]
	v_pk_fma_f32 v[102:103], v[14:15], v[106:107], v[108:109]
	v_lshlrev_b32_e32 v106, 16, v35
	v_and_b32_e32 v107, 0xffff0000, v35
	v_lshlrev_b32_e32 v108, 16, v27
	v_and_b32_e32 v109, 0xffff0000, v27
	v_pk_mul_f32 v[106:107], v[96:97], v[106:107] op_sel_hi:[0,1]
	v_pk_fma_f32 v[104:105], v[16:17], v[106:107], v[108:109]
	global_store_dwordx4 v23, v[98:101], s[6:7]
	global_store_dwordx4 v23, v[102:105], s[6:7] offset:16
	v_lshlrev_b32_e32 v106, 16, v36
	v_and_b32_e32 v107, 0xffff0000, v36
	v_lshlrev_b32_e32 v108, 16, v28
	v_and_b32_e32 v109, 0xffff0000, v28
	v_pk_mul_f32 v[106:107], v[96:97], v[106:107] op_sel_hi:[0,1]
	v_pk_fma_f32 v[98:99], v[2:3], v[106:107], v[108:109]
	v_lshlrev_b32_e32 v106, 16, v37
	v_and_b32_e32 v107, 0xffff0000, v37
	v_lshlrev_b32_e32 v108, 16, v29
	v_and_b32_e32 v109, 0xffff0000, v29
	v_pk_mul_f32 v[106:107], v[96:97], v[106:107] op_sel_hi:[0,1]
	v_pk_fma_f32 v[100:101], v[4:5], v[106:107], v[108:109]
	v_lshlrev_b32_e32 v106, 16, v38
	v_and_b32_e32 v107, 0xffff0000, v38
	v_lshlrev_b32_e32 v108, 16, v30
	v_and_b32_e32 v109, 0xffff0000, v30
	v_pk_mul_f32 v[106:107], v[96:97], v[106:107] op_sel_hi:[0,1]
	v_pk_fma_f32 v[102:103], v[6:7], v[106:107], v[108:109]
	v_lshlrev_b32_e32 v106, 16, v39
	v_and_b32_e32 v107, 0xffff0000, v39
	v_lshlrev_b32_e32 v108, 16, v31
	v_and_b32_e32 v109, 0xffff0000, v31
	v_pk_mul_f32 v[106:107], v[96:97], v[106:107] op_sel_hi:[0,1]
	v_pk_fma_f32 v[104:105], v[8:9], v[106:107], v[108:109]
	global_store_dwordx4 v23, v[98:101], s[6:7] offset:2048
	global_store_dwordx4 v23, v[102:105], s[6:7] offset:2064
	v_add_u32_e32 v18, 0x7ff800, v18
	v_add_u32_e32 v20, 0x7ff800, v20
	v_add_u32_e32 v21, 0x3ffc, v21
	global_load_dwordx4 v[24:27], v18, s[4:5]
	global_load_dwordx4 v[32:35], v20, s[6:7]
	global_load_dwordx4 v[28:31], v18, s[4:5] offset:1024
	global_load_dwordx4 v[36:39], v20, s[6:7] offset:1024
	global_load_dword v40, v21, s[4:5]
	s_waitcnt vmcnt(19)
; __device__ __forceinline__ float bflo(unsigned w) { return __uint_as_float(w << 16); }
; __device__ __forceinline__ float bfhi(unsigned w) { return __uint_as_float(w & 0xffff0000u); }
; __device__ __forceinline__ void resid_rows(bf16_t* R, const bf16_t* Y, const float* ssqY, const float* g, float* rstd_out, float* outf, bool wf32, int row_lo, int row_hi, int yoff, int gw, int NGW, int lane) {
;     ...
;         for (int k = 0; k < RP; ++k) { const int row = row0 + k * NGW; const bool ok = row < row_hi; const int rw = ok ? row : row0;
;             ssv[k] = ssqY[rw];
; #pragma unroll
;             for (int j = 0; j < 2; ++j) { const int c = 8 * lane + 512 * j; rr[k][j] = *(const u32x4*)(R + (size_t)rw * DM + c); oo[k][j] = *(const u32x4*)(Y + (size_t)(rw - yoff) * DM + c); } }
;     ...
;         for (int k = 0; k < RP; ++k) { const int row = row0 + k * NGW; if (row < row_hi) {
;             const float rs = __builtin_amdgcn_rsqf(ssv[k] * (1.0f / DM) + RMS_EPS); float s = 0.f;
; #pragma unroll
;             for (int j = 0; j < 2; ++j) { const int c = 8 * lane + 512 * j; const u32x4 r = rr[k][j], o = oo[k][j]; const f32x4 ga = gv[j][0], gb = gv[j][1];
;                 f32x4 ya, yb; ya[0] = bflo(r.x) + bflo(o.x) * rs * ga[0]; ya[1] = bfhi(r.x) + bfhi(o.x) * rs * ga[1]; ya[2] = bflo(r.y) + bflo(o.y) * rs * ga[2]; ya[3] = bfhi(r.y) + bfhi(o.y) * rs * ga[3];
;                 yb[0] = bflo(r.z) + bflo(o.z) * rs * gb[0]; yb[1] = bfhi(r.z) + bfhi(o.z) * rs * gb[1]; yb[2] = bflo(r.w) + bflo(o.w) * rs * gb[2]; yb[3] = bfhi(r.w) + bfhi(o.w) * rs * gb[3];
;                 if (wf32) { *(f32x4*)(outf + (size_t)row * DM + c) = ya; *(f32x4*)(outf + (size_t)row * DM + c + 4) = yb; }
;                 s += (ya[0] * ya[0] + ya[1] * ya[1]) + (ya[2] * ya[2] + ya[3] * ya[3]) + (yb[0] * yb[0] + yb[1] * yb[1]) + (yb[2] * yb[2] + yb[3] * yb[3]);
;                 u32x4 w; w.x = pk2(ya[0], ya[1]); w.y = pk2(ya[2], ya[3]); w.z = pk2(yb[0], yb[1]); w.w = pk2(yb[2], yb[3]); *(u32x4*)(R + (size_t)row * DM + c) = w; }
	v_fmamk_f32 v96, v58, 0x3a800000, v244
	v_rsq_f32_e32 v96, v96
	v_add_u32_e32 v23, 0x1000, v23
	v_lshlrev_b32_e32 v106, 16, v50
	v_and_b32_e32 v107, 0xffff0000, v50
	v_lshlrev_b32_e32 v108, 16, v42
	v_and_b32_e32 v109, 0xffff0000, v42
	v_pk_mul_f32 v[106:107], v[96:97], v[106:107] op_sel_hi:[0,1]
	v_pk_fma_f32 v[98:99], v[10:11], v[106:107], v[108:109]
	v_lshlrev_b32_e32 v106, 16, v51
	v_and_b32_e32 v107, 0xffff0000, v51
	v_lshlrev_b32_e32 v108, 16, v43
	v_and_b32_e32 v109, 0xffff0000, v43
	v_pk_mul_f32 v[106:107], v[96:97], v[106:107] op_sel_hi:[0,1]
	v_pk_fma_f32 v[100:101], v[12:13], v[106:107], v[108:109]
	v_lshlrev_b32_e32 v106, 16, v52
	v_and_b32_e32 v107, 0xffff0000, v52
	v_lshlrev_b32_e32 v108, 16, v44
	v_and_b32_e32 v109, 0xffff0000, v44
	v_pk_mul_f32 v[106:107], v[96:97], v[106:107] op_sel_hi:[0,1]
	v_pk_fma_f32 v[102:103], v[14:15], v[106:107], v[108:109]
	v_lshlrev_b32_e32 v106, 16, v53
	v_and_b32_e32 v107, 0xffff0000, v53
	v_lshlrev_b32_e32 v108, 16, v45
	v_and_b32_e32 v109, 0xffff0000, v45
	v_pk_mul_f32 v[106:107], v[96:97], v[106:107] op_sel_hi:[0,1]
	v_pk_fma_f32 v[104:105], v[16:17], v[106:107], v[108:109]
	global_store_dwordx4 v23, v[98:101], s[6:7]
	global_store_dwordx4 v23, v[102:105], s[6:7] offset:16
	v_lshlrev_b32_e32 v106, 16, v54
	v_and_b32_e32 v107, 0xffff0000, v54
	v_lshlrev_b32_e32 v108, 16, v46
	v_and_b32_e32 v109, 0xffff0000, v46
	v_pk_mul_f32 v[106:107], v[96:97], v[106:107] op_sel_hi:[0,1]
	v_pk_fma_f32 v[98:99], v[2:3], v[106:107], v[108:109]
	v_lshlrev_b32_e32 v106, 16, v55
	v_and_b32_e32 v107, 0xffff0000, v55
	v_lshlrev_b32_e32 v108, 16, v47
	v_and_b32_e32 v109, 0xffff0000, v47
	v_pk_mul_f32 v[106:107], v[96:97], v[106:107] op_sel_hi:[0,1]
	v_pk_fma_f32 v[100:101], v[4:5], v[106:107], v[108:109]
	v_lshlrev_b32_e32 v106, 16, v56
	v_and_b32_e32 v107, 0xffff0000, v56
	v_lshlrev_b32_e32 v108, 16, v48
	v_and_b32_e32 v109, 0xffff0000, v48
	v_pk_mul_f32 v[106:107], v[96:97], v[106:107] op_sel_hi:[0,1]
	v_pk_fma_f32 v[102:103], v[6:7], v[106:107], v[108:109]
	v_lshlrev_b32_e32 v106, 16, v57
	v_and_b32_e32 v107, 0xffff0000, v57
	v_lshlrev_b32_e32 v108, 16, v49
	v_and_b32_e32 v109, 0xffff0000, v49
	v_pk_mul_f32 v[106:107], v[96:97], v[106:107] op_sel_hi:[0,1]
	v_pk_fma_f32 v[104:105], v[8:9], v[106:107], v[108:109]
	global_store_dwordx4 v23, v[98:101], s[6:7] offset:2048
	global_store_dwordx4 v23, v[102:105], s[6:7] offset:2064
	v_add_u32_e32 v18, 0x800, v18
	v_add_u32_e32 v20, 0x800, v20
	v_add_u32_e32 v21, 0x4, v21
	global_load_dwordx4 v[42:45], v18, s[4:5]
	global_load_dwordx4 v[50:53], v20, s[6:7]
	global_load_dwordx4 v[46:49], v18, s[4:5] offset:1024
	global_load_dwordx4 v[54:57], v20, s[6:7] offset:1024
	global_load_dword v58, v21, s[4:5]
	s_waitcnt vmcnt(23)
	v_fmamk_f32 v96, v76, 0x3a800000, v244
	v_rsq_f32_e32 v96, v96
	v_add_u32_e32 v23, 0xfff000, v23
	v_lshlrev_b32_e32 v106, 16, v68
	v_and_b32_e32 v107, 0xffff0000, v68
	v_lshlrev_b32_e32 v108, 16, v60
	v_and_b32_e32 v109, 0xffff0000, v60
	v_pk_mul_f32 v[106:107], v[96:97], v[106:107] op_sel_hi:[0,1]
	v_pk_fma_f32 v[98:99], v[10:11], v[106:107], v[108:109]
	v_lshlrev_b32_e32 v106, 16, v69
	v_and_b32_e32 v107, 0xffff0000, v69
	v_lshlrev_b32_e32 v108, 16, v61
	v_and_b32_e32 v109, 0xffff0000, v61
	v_pk_mul_f32 v[106:107], v[96:97], v[106:107] op_sel_hi:[0,1]
	v_pk_fma_f32 v[100:101], v[12:13], v[106:107], v[108:109]
	v_lshlrev_b32_e32 v106, 16, v70
	v_and_b32_e32 v107, 0xffff0000, v70
	v_lshlrev_b32_e32 v108, 16, v62
	v_and_b32_e32 v109, 0xffff0000, v62
	v_pk_mul_f32 v[106:107], v[96:97], v[106:107] op_sel_hi:[0,1]
	v_pk_fma_f32 v[102:103], v[14:15], v[106:107], v[108:109]
	v_lshlrev_b32_e32 v106, 16, v71
	v_and_b32_e32 v107, 0xffff0000, v71
	v_lshlrev_b32_e32 v108, 16, v63
	v_and_b32_e32 v109, 0xffff0000, v63
	v_pk_mul_f32 v[106:107], v[96:97], v[106:107] op_sel_hi:[0,1]
	v_pk_fma_f32 v[104:105], v[16:17], v[106:107], v[108:109]
	global_store_dwordx4 v23, v[98:101], s[6:7]
	global_store_dwordx4 v23, v[102:105], s[6:7] offset:16
	v_lshlrev_b32_e32 v106, 16, v72
	v_and_b32_e32 v107, 0xffff0000, v72
	v_lshlrev_b32_e32 v108, 16, v64
	v_and_b32_e32 v109, 0xffff0000, v64
	v_pk_mul_f32 v[106:107], v[96:97], v[106:107] op_sel_hi:[0,1]
	v_pk_fma_f32 v[98:99], v[2:3], v[106:107], v[108:109]
	v_lshlrev_b32_e32 v106, 16, v73
	v_and_b32_e32 v107, 0xffff0000, v73
	v_lshlrev_b32_e32 v108, 16, v65
	v_and_b32_e32 v109, 0xffff0000, v65
	v_pk_mul_f32 v[106:107], v[96:97], v[106:107] op_sel_hi:[0,1]
	v_pk_fma_f32 v[100:101], v[4:5], v[106:107], v[108:109]
	v_lshlrev_b32_e32 v106, 16, v74
	v_and_b32_e32 v107, 0xffff0000, v74
	v_lshlrev_b32_e32 v108, 16, v66
	v_and_b32_e32 v109, 0xffff0000, v66
	v_pk_mul_f32 v[106:107], v[96:97], v[106:107] op_sel_hi:[0,1]
	v_pk_fma_f32 v[102:103], v[6:7], v[106:107], v[108:109]
	v_lshlrev_b32_e32 v106, 16, v75
	v_and_b32_e32 v107, 0xffff0000, v75
	v_lshlrev_b32_e32 v108, 16, v67
	v_and_b32_e32 v109, 0xffff0000, v67
	v_pk_mul_f32 v[106:107], v[96:97], v[106:107] op_sel_hi:[0,1]
	v_pk_fma_f32 v[104:105], v[8:9], v[106:107], v[108:109]
	global_store_dwordx4 v23, v[98:101], s[6:7] offset:2048
	global_store_dwordx4 v23, v[102:105], s[6:7] offset:2064
	v_add_u32_e32 v18, 0x7ff800, v18
	v_add_u32_e32 v20, 0x7ff800, v20
	v_add_u32_e32 v21, 0x3ffc, v21
	global_load_dwordx4 v[60:63], v18, s[4:5]
	global_load_dwordx4 v[68:71], v20, s[6:7]
	global_load_dwordx4 v[64:67], v18, s[4:5] offset:1024
	global_load_dwordx4 v[72:75], v20, s[6:7] offset:1024
	global_load_dword v76, v21, s[4:5]
	s_waitcnt vmcnt(27)
; __device__ __forceinline__ float bflo(unsigned w) { return __uint_as_float(w << 16); }
; __device__ __forceinline__ float bfhi(unsigned w) { return __uint_as_float(w & 0xffff0000u); }
; __device__ __forceinline__ void resid_rows(bf16_t* R, const bf16_t* Y, const float* ssqY, const float* g, float* rstd_out, float* outf, bool wf32, int row_lo, int row_hi, int yoff, int gw, int NGW, int lane) {
;     ...
;         for (int k = 0; k < RP; ++k) { const int row = row0 + k * NGW; const bool ok = row < row_hi; const int rw = ok ? row : row0;
;             ssv[k] = ssqY[rw];
; #pragma unroll
;             for (int j = 0; j < 2; ++j) { const int c = 8 * lane + 512 * j; rr[k][j] = *(const u32x4*)(R + (size_t)rw * DM + c); oo[k][j] = *(const u32x4*)(Y + (size_t)(rw - yoff) * DM + c); } }
;     ...
;         for (int k = 0; k < RP; ++k) { const int row = row0 + k * NGW; if (row < row_hi) {
;             const float rs = __builtin_amdgcn_rsqf(ssv[k] * (1.0f / DM) + RMS_EPS); float s = 0.f;
; #pragma unroll
;             for (int j = 0; j < 2; ++j) { const int c = 8 * lane + 512 * j; const u32x4 r = rr[k][j], o = oo[k][j]; const f32x4 ga = gv[j][0], gb = gv[j][1];
;                 f32x4 ya, yb; ya[0] = bflo(r.x) + bflo(o.x) * rs * ga[0]; ya[1] = bfhi(r.x) + bfhi(o.x) * rs * ga[1]; ya[2] = bflo(r.y) + bflo(o.y) * rs * ga[2]; ya[3] = bfhi(r.y) + bfhi(o.y) * rs * ga[3];
;                 yb[0] = bflo(r.z) + bflo(o.z) * rs * gb[0]; yb[1] = bfhi(r.z) + bfhi(o.z) * rs * gb[1]; yb[2] = bflo(r.w) + bflo(o.w) * rs * gb[2]; yb[3] = bfhi(r.w) + bfhi(o.w) * rs * gb[3];
;                 if (wf32) { *(f32x4*)(outf + (size_t)row * DM + c) = ya; *(f32x4*)(outf + (size_t)row * DM + c + 4) = yb; }
;                 s += (ya[0] * ya[0] + ya[1] * ya[1]) + (ya[2] * ya[2] + ya[3] * ya[3]) + (yb[0] * yb[0] + yb[1] * yb[1]) + (yb[2] * yb[2] + yb[3] * yb[3]);
;                 u32x4 w; w.x = pk2(ya[0], ya[1]); w.y = pk2(ya[2], ya[3]); w.z = pk2(yb[0], yb[1]); w.w = pk2(yb[2], yb[3]); *(u32x4*)(R + (size_t)row * DM + c) = w; }
	v_fmamk_f32 v96, v94, 0x3a800000, v244
	v_rsq_f32_e32 v96, v96
	v_add_u32_e32 v23, 0x1000, v23
	v_lshlrev_b32_e32 v106, 16, v86
	v_and_b32_e32 v107, 0xffff0000, v86
	v_lshlrev_b32_e32 v108, 16, v78
	v_and_b32_e32 v109, 0xffff0000, v78
	v_pk_mul_f32 v[106:107], v[96:97], v[106:107] op_sel_hi:[0,1]
	v_pk_fma_f32 v[98:99], v[10:11], v[106:107], v[108:109]
	v_lshlrev_b32_e32 v106, 16, v87
	v_and_b32_e32 v107, 0xffff0000, v87
	v_lshlrev_b32_e32 v108, 16, v79
	v_and_b32_e32 v109, 0xffff0000, v79
	v_pk_mul_f32 v[106:107], v[96:97], v[106:107] op_sel_hi:[0,1]
	v_pk_fma_f32 v[100:101], v[12:13], v[106:107], v[108:109]
	v_lshlrev_b32_e32 v106, 16, v88
	v_and_b32_e32 v107, 0xffff0000, v88
	v_lshlrev_b32_e32 v108, 16, v80
	v_and_b32_e32 v109, 0xffff0000, v80
	v_pk_mul_f32 v[106:107], v[96:97], v[106:107] op_sel_hi:[0,1]
	v_pk_fma_f32 v[102:103], v[14:15], v[106:107], v[108:109]
	v_lshlrev_b32_e32 v106, 16, v89
	v_and_b32_e32 v107, 0xffff0000, v89
	v_lshlrev_b32_e32 v108, 16, v81
	v_and_b32_e32 v109, 0xffff0000, v81
	v_pk_mul_f32 v[106:107], v[96:97], v[106:107] op_sel_hi:[0,1]
	v_pk_fma_f32 v[104:105], v[16:17], v[106:107], v[108:109]
	global_store_dwordx4 v23, v[98:101], s[6:7]
	global_store_dwordx4 v23, v[102:105], s[6:7] offset:16
	v_lshlrev_b32_e32 v106, 16, v90
	v_and_b32_e32 v107, 0xffff0000, v90
	v_lshlrev_b32_e32 v108, 16, v82
	v_and_b32_e32 v109, 0xffff0000, v82
	v_pk_mul_f32 v[106:107], v[96:97], v[106:107] op_sel_hi:[0,1]
	v_pk_fma_f32 v[98:99], v[2:3], v[106:107], v[108:109]
	v_lshlrev_b32_e32 v106, 16, v91
	v_and_b32_e32 v107, 0xffff0000, v91
	v_lshlrev_b32_e32 v108, 16, v83
	v_and_b32_e32 v109, 0xffff0000, v83
	v_pk_mul_f32 v[106:107], v[96:97], v[106:107] op_sel_hi:[0,1]
	v_pk_fma_f32 v[100:101], v[4:5], v[106:107], v[108:109]
	v_lshlrev_b32_e32 v106, 16, v92
	v_and_b32_e32 v107, 0xffff0000, v92
	v_lshlrev_b32_e32 v108, 16, v84
	v_and_b32_e32 v109, 0xffff0000, v84
	v_pk_mul_f32 v[106:107], v[96:97], v[106:107] op_sel_hi:[0,1]
	v_pk_fma_f32 v[102:103], v[6:7], v[106:107], v[108:109]
	v_lshlrev_b32_e32 v106, 16, v93
	v_and_b32_e32 v107, 0xffff0000, v93
	v_lshlrev_b32_e32 v108, 16, v85
	v_and_b32_e32 v109, 0xffff0000, v85
	v_pk_mul_f32 v[106:107], v[96:97], v[106:107] op_sel_hi:[0,1]
	v_pk_fma_f32 v[104:105], v[8:9], v[106:107], v[108:109]
	global_store_dwordx4 v23, v[98:101], s[6:7] offset:2048
	global_store_dwordx4 v23, v[102:105], s[6:7] offset:2064
	v_add_u32_e32 v18, 0x800, v18
	v_add_u32_e32 v20, 0x800, v20
	v_add_u32_e32 v21, 0x4, v21
	global_load_dwordx4 v[78:81], v18, s[4:5]
	global_load_dwordx4 v[86:89], v20, s[6:7]
	global_load_dwordx4 v[82:85], v18, s[4:5] offset:1024
	global_load_dwordx4 v[90:93], v20, s[6:7] offset:1024
	global_load_dword v94, v21, s[4:5]
	s_waitcnt vmcnt(27)
	v_fmamk_f32 v96, v40, 0x3a800000, v244
	v_rsq_f32_e32 v96, v96
	v_add_u32_e32 v23, 0xfff000, v23
	v_lshlrev_b32_e32 v106, 16, v32
	v_and_b32_e32 v107, 0xffff0000, v32
	v_lshlrev_b32_e32 v108, 16, v24
	v_and_b32_e32 v109, 0xffff0000, v24
	v_pk_mul_f32 v[106:107], v[96:97], v[106:107] op_sel_hi:[0,1]
	v_pk_fma_f32 v[98:99], v[10:11], v[106:107], v[108:109]
	v_lshlrev_b32_e32 v106, 16, v33
	v_and_b32_e32 v107, 0xffff0000, v33
	v_lshlrev_b32_e32 v108, 16, v25
	v_and_b32_e32 v109, 0xffff0000, v25
	v_pk_mul_f32 v[106:107], v[96:97], v[106:107] op_sel_hi:[0,1]
	v_pk_fma_f32 v[100:101], v[12:13], v[106:107], v[108:109]
	v_lshlrev_b32_e32 v106, 16, v34
	v_and_b32_e32 v107, 0xffff0000, v34
	v_lshlrev_b32_e32 v108, 16, v26
	v_and_b32_e32 v109, 0xffff0000, v26
	v_pk_mul_f32 v[106:107], v[96:97], v[106:107] op_sel_hi:[0,1]
	v_pk_fma_f32 v[102:103], v[14:15], v[106:107], v[108:109]
	v_lshlrev_b32_e32 v106, 16, v35
	v_and_b32_e32 v107, 0xffff0000, v35
	v_lshlrev_b32_e32 v108, 16, v27
	v_and_b32_e32 v109, 0xffff0000, v27
	v_pk_mul_f32 v[106:107], v[96:97], v[106:107] op_sel_hi:[0,1]
	v_pk_fma_f32 v[104:105], v[16:17], v[106:107], v[108:109]
	global_store_dwordx4 v23, v[98:101], s[6:7]
	global_store_dwordx4 v23, v[102:105], s[6:7] offset:16
	v_lshlrev_b32_e32 v106, 16, v36
	v_and_b32_e32 v107, 0xffff0000, v36
	v_lshlrev_b32_e32 v108, 16, v28
	v_and_b32_e32 v109, 0xffff0000, v28
	v_pk_mul_f32 v[106:107], v[96:97], v[106:107] op_sel_hi:[0,1]
	v_pk_fma_f32 v[98:99], v[2:3], v[106:107], v[108:109]
	v_lshlrev_b32_e32 v106, 16, v37
	v_and_b32_e32 v107, 0xffff0000, v37
	v_lshlrev_b32_e32 v108, 16, v29
	v_and_b32_e32 v109, 0xffff0000, v29
	v_pk_mul_f32 v[106:107], v[96:97], v[106:107] op_sel_hi:[0,1]
	v_pk_fma_f32 v[100:101], v[4:5], v[106:107], v[108:109]
	v_lshlrev_b32_e32 v106, 16, v38
	v_and_b32_e32 v107, 0xffff0000, v38
	v_lshlrev_b32_e32 v108, 16, v30
	v_and_b32_e32 v109, 0xffff0000, v30
	v_pk_mul_f32 v[106:107], v[96:97], v[106:107] op_sel_hi:[0,1]
	v_pk_fma_f32 v[102:103], v[6:7], v[106:107], v[108:109]
	v_lshlrev_b32_e32 v106, 16, v39
	v_and_b32_e32 v107, 0xffff0000, v39
	v_lshlrev_b32_e32 v108, 16, v31
	v_and_b32_e32 v109, 0xffff0000, v31
	v_pk_mul_f32 v[106:107], v[96:97], v[106:107] op_sel_hi:[0,1]
	v_pk_fma_f32 v[104:105], v[8:9], v[106:107], v[108:109]
	global_store_dwordx4 v23, v[98:101], s[6:7] offset:2048
	global_store_dwordx4 v23, v[102:105], s[6:7] offset:2064
	v_add_u32_e32 v18, 0xfc7ff800, v18
	s_lshl_b32 s18, s13, 11
	v_subrev_u32_e32 v18, s18, v18
	v_add_u32_e32 v20, 0xb7ff800, v20
	s_lshl_b32 s18, s13, 11
	v_subrev_u32_e32 v20, s18, v20
	v_add_u32_e32 v21, 0xfffe3ffc, v21
	s_lshl_b32 s18, s13, 2
	v_subrev_u32_e32 v21, s18, v21
	global_load_dwordx4 v[24:27], v18, s[4:5]
	global_load_dwordx4 v[32:35], v20, s[4:5]
	global_load_dwordx4 v[28:31], v18, s[4:5] offset:1024
	global_load_dwordx4 v[36:39], v20, s[4:5] offset:1024
	global_load_dword v40, v21, s[4:5]
	s_waitcnt vmcnt(27)
; __device__ __forceinline__ float bflo(unsigned w) { return __uint_as_float(w << 16); }
; __device__ __forceinline__ float bfhi(unsigned w) { return __uint_as_float(w & 0xffff0000u); }
; __device__ __forceinline__ void resid_rows(bf16_t* R, const bf16_t* Y, const float* ssqY, const float* g, float* rstd_out, float* outf, bool wf32, int row_lo, int row_hi, int yoff, int gw, int NGW, int lane) {
;     ...
;         for (int k = 0; k < RP; ++k) { const int row = row0 + k * NGW; const bool ok = row < row_hi; const int rw = ok ? row : row0;
;             ssv[k] = ssqY[rw];
; #pragma unroll
;             for (int j = 0; j < 2; ++j) { const int c = 8 * lane + 512 * j; rr[k][j] = *(const u32x4*)(R + (size_t)rw * DM + c); oo[k][j] = *(const u32x4*)(Y + (size_t)(rw - yoff) * DM + c); } }
;     ...
;         for (int k = 0; k < RP; ++k) { const int row = row0 + k * NGW; if (row < row_hi) {
;             const float rs = __builtin_amdgcn_rsqf(ssv[k] * (1.0f / DM) + RMS_EPS); float s = 0.f;
; #pragma unroll
;             for (int j = 0; j < 2; ++j) { const int c = 8 * lane + 512 * j; const u32x4 r = rr[k][j], o = oo[k][j]; const f32x4 ga = gv[j][0], gb = gv[j][1];
;                 f32x4 ya, yb; ya[0] = bflo(r.x) + bflo(o.x) * rs * ga[0]; ya[1] = bfhi(r.x) + bfhi(o.x) * rs * ga[1]; ya[2] = bflo(r.y) + bflo(o.y) * rs * ga[2]; ya[3] = bfhi(r.y) + bfhi(o.y) * rs * ga[3];
;                 yb[0] = bflo(r.z) + bflo(o.z) * rs * gb[0]; yb[1] = bfhi(r.z) + bfhi(o.z) * rs * gb[1]; yb[2] = bflo(r.w) + bflo(o.w) * rs * gb[2]; yb[3] = bfhi(r.w) + bfhi(o.w) * rs * gb[3];
;                 if (wf32) { *(f32x4*)(outf + (size_t)row * DM + c) = ya; *(f32x4*)(outf + (size_t)row * DM + c + 4) = yb; }
;                 s += (ya[0] * ya[0] + ya[1] * ya[1]) + (ya[2] * ya[2] + ya[3] * ya[3]) + (yb[0] * yb[0] + yb[1] * yb[1]) + (yb[2] * yb[2] + yb[3] * yb[3]);
;                 u32x4 w; w.x = pk2(ya[0], ya[1]); w.y = pk2(ya[2], ya[3]); w.z = pk2(yb[0], yb[1]); w.w = pk2(yb[2], yb[3]); *(u32x4*)(R + (size_t)row * DM + c) = w; }
	v_fmamk_f32 v96, v58, 0x3a800000, v244
	v_rsq_f32_e32 v96, v96
	v_add_u32_e32 v23, 0x1000, v23
	v_lshlrev_b32_e32 v106, 16, v50
	v_and_b32_e32 v107, 0xffff0000, v50
	v_lshlrev_b32_e32 v108, 16, v42
	v_and_b32_e32 v109, 0xffff0000, v42
	v_pk_mul_f32 v[106:107], v[96:97], v[106:107] op_sel_hi:[0,1]
	v_pk_fma_f32 v[98:99], v[10:11], v[106:107], v[108:109]
	v_lshlrev_b32_e32 v106, 16, v51
	v_and_b32_e32 v107, 0xffff0000, v51
	v_lshlrev_b32_e32 v108, 16, v43
	v_and_b32_e32 v109, 0xffff0000, v43
	v_pk_mul_f32 v[106:107], v[96:97], v[106:107] op_sel_hi:[0,1]
	v_pk_fma_f32 v[100:101], v[12:13], v[106:107], v[108:109]
	v_lshlrev_b32_e32 v106, 16, v52
	v_and_b32_e32 v107, 0xffff0000, v52
	v_lshlrev_b32_e32 v108, 16, v44
	v_and_b32_e32 v109, 0xffff0000, v44
	v_pk_mul_f32 v[106:107], v[96:97], v[106:107] op_sel_hi:[0,1]
	v_pk_fma_f32 v[102:103], v[14:15], v[106:107], v[108:109]
	v_lshlrev_b32_e32 v106, 16, v53
	v_and_b32_e32 v107, 0xffff0000, v53
	v_lshlrev_b32_e32 v108, 16, v45
	v_and_b32_e32 v109, 0xffff0000, v45
	v_pk_mul_f32 v[106:107], v[96:97], v[106:107] op_sel_hi:[0,1]
	v_pk_fma_f32 v[104:105], v[16:17], v[106:107], v[108:109]
	global_store_dwordx4 v23, v[98:101], s[6:7]
	global_store_dwordx4 v23, v[102:105], s[6:7] offset:16
	v_lshlrev_b32_e32 v106, 16, v54
	v_and_b32_e32 v107, 0xffff0000, v54
	v_lshlrev_b32_e32 v108, 16, v46
	v_and_b32_e32 v109, 0xffff0000, v46
	v_pk_mul_f32 v[106:107], v[96:97], v[106:107] op_sel_hi:[0,1]
	v_pk_fma_f32 v[98:99], v[2:3], v[106:107], v[108:109]
	v_lshlrev_b32_e32 v106, 16, v55
	v_and_b32_e32 v107, 0xffff0000, v55
	v_lshlrev_b32_e32 v108, 16, v47
	v_and_b32_e32 v109, 0xffff0000, v47
	v_pk_mul_f32 v[106:107], v[96:97], v[106:107] op_sel_hi:[0,1]
	v_pk_fma_f32 v[100:101], v[4:5], v[106:107], v[108:109]
	v_lshlrev_b32_e32 v106, 16, v56
	v_and_b32_e32 v107, 0xffff0000, v56
	v_lshlrev_b32_e32 v108, 16, v48
	v_and_b32_e32 v109, 0xffff0000, v48
	v_pk_mul_f32 v[106:107], v[96:97], v[106:107] op_sel_hi:[0,1]
	v_pk_fma_f32 v[102:103], v[6:7], v[106:107], v[108:109]
	v_lshlrev_b32_e32 v106, 16, v57
	v_and_b32_e32 v107, 0xffff0000, v57
	v_lshlrev_b32_e32 v108, 16, v49
	v_and_b32_e32 v109, 0xffff0000, v49
	v_pk_mul_f32 v[106:107], v[96:97], v[106:107] op_sel_hi:[0,1]
	v_pk_fma_f32 v[104:105], v[8:9], v[106:107], v[108:109]
	global_store_dwordx4 v23, v[98:101], s[6:7] offset:2048
	global_store_dwordx4 v23, v[102:105], s[6:7] offset:2064
	v_add_u32_e32 v18, 0x400000, v18
	v_add_u32_e32 v20, 0x400000, v20
	v_add_u32_e32 v21, 0x2000, v21
	global_load_dwordx4 v[42:45], v18, s[4:5]
	global_load_dwordx4 v[50:53], v20, s[4:5]
	global_load_dwordx4 v[46:49], v18, s[4:5] offset:1024
	global_load_dwordx4 v[54:57], v20, s[4:5] offset:1024
	global_load_dword v58, v21, s[4:5]
	s_waitcnt vmcnt(27)
	v_fmamk_f32 v96, v76, 0x3a800000, v244
	v_rsq_f32_e32 v96, v96
	v_add_u32_e32 v23, 0xfff000, v23
	v_lshlrev_b32_e32 v106, 16, v68
	v_and_b32_e32 v107, 0xffff0000, v68
	v_lshlrev_b32_e32 v108, 16, v60
	v_and_b32_e32 v109, 0xffff0000, v60
	v_pk_mul_f32 v[106:107], v[96:97], v[106:107] op_sel_hi:[0,1]
	v_pk_fma_f32 v[98:99], v[10:11], v[106:107], v[108:109]
	v_lshlrev_b32_e32 v106, 16, v69
	v_and_b32_e32 v107, 0xffff0000, v69
	v_lshlrev_b32_e32 v108, 16, v61
	v_and_b32_e32 v109, 0xffff0000, v61
	v_pk_mul_f32 v[106:107], v[96:97], v[106:107] op_sel_hi:[0,1]
	v_pk_fma_f32 v[100:101], v[12:13], v[106:107], v[108:109]
	v_lshlrev_b32_e32 v106, 16, v70
	v_and_b32_e32 v107, 0xffff0000, v70
	v_lshlrev_b32_e32 v108, 16, v62
	v_and_b32_e32 v109, 0xffff0000, v62
	v_pk_mul_f32 v[106:107], v[96:97], v[106:107] op_sel_hi:[0,1]
	v_pk_fma_f32 v[102:103], v[14:15], v[106:107], v[108:109]
	v_lshlrev_b32_e32 v106, 16, v71
	v_and_b32_e32 v107, 0xffff0000, v71
	v_lshlrev_b32_e32 v108, 16, v63
	v_and_b32_e32 v109, 0xffff0000, v63
	v_pk_mul_f32 v[106:107], v[96:97], v[106:107] op_sel_hi:[0,1]
	v_pk_fma_f32 v[104:105], v[16:17], v[106:107], v[108:109]
	global_store_dwordx4 v23, v[98:101], s[6:7]
	global_store_dwordx4 v23, v[102:105], s[6:7] offset:16
	v_lshlrev_b32_e32 v106, 16, v72
	v_and_b32_e32 v107, 0xffff0000, v72
	v_lshlrev_b32_e32 v108, 16, v64
	v_and_b32_e32 v109, 0xffff0000, v64
	v_pk_mul_f32 v[106:107], v[96:97], v[106:107] op_sel_hi:[0,1]
	v_pk_fma_f32 v[98:99], v[2:3], v[106:107], v[108:109]
	v_lshlrev_b32_e32 v106, 16, v73
	v_and_b32_e32 v107, 0xffff0000, v73
	v_lshlrev_b32_e32 v108, 16, v65
	v_and_b32_e32 v109, 0xffff0000, v65
	v_pk_mul_f32 v[106:107], v[96:97], v[106:107] op_sel_hi:[0,1]
	v_pk_fma_f32 v[100:101], v[4:5], v[106:107], v[108:109]
	v_lshlrev_b32_e32 v106, 16, v74
	v_and_b32_e32 v107, 0xffff0000, v74
	v_lshlrev_b32_e32 v108, 16, v66
	v_and_b32_e32 v109, 0xffff0000, v66
	v_pk_mul_f32 v[106:107], v[96:97], v[106:107] op_sel_hi:[0,1]
	v_pk_fma_f32 v[102:103], v[6:7], v[106:107], v[108:109]
	v_lshlrev_b32_e32 v106, 16, v75
	v_and_b32_e32 v107, 0xffff0000, v75
	v_lshlrev_b32_e32 v108, 16, v67
	v_and_b32_e32 v109, 0xffff0000, v67
	v_pk_mul_f32 v[106:107], v[96:97], v[106:107] op_sel_hi:[0,1]
	v_pk_fma_f32 v[104:105], v[8:9], v[106:107], v[108:109]
	global_store_dwordx4 v23, v[98:101], s[6:7] offset:2048
	global_store_dwordx4 v23, v[102:105], s[6:7] offset:2064
	v_add_u32_e32 v18, 0x400000, v18
	v_add_u32_e32 v20, 0x400000, v20
	v_add_u32_e32 v21, 0x2000, v21
	global_load_dwordx4 v[60:63], v18, s[4:5]
	global_load_dwordx4 v[68:71], v20, s[4:5]
	global_load_dwordx4 v[64:67], v18, s[4:5] offset:1024
	global_load_dwordx4 v[72:75], v20, s[4:5] offset:1024
	global_load_dword v76, v21, s[4:5]
	s_waitcnt vmcnt(27)
; __device__ __forceinline__ float bflo(unsigned w) { return __uint_as_float(w << 16); }
; __device__ __forceinline__ float bfhi(unsigned w) { return __uint_as_float(w & 0xffff0000u); }
; __device__ __forceinline__ void resid_rows(bf16_t* R, const bf16_t* Y, const float* ssqY, const float* g, float* rstd_out, float* outf, bool wf32, int row_lo, int row_hi, int yoff, int gw, int NGW, int lane) {
;     ...
;         for (int k = 0; k < RP; ++k) { const int row = row0 + k * NGW; const bool ok = row < row_hi; const int rw = ok ? row : row0;
;             ssv[k] = ssqY[rw];
; #pragma unroll
;             for (int j = 0; j < 2; ++j) { const int c = 8 * lane + 512 * j; rr[k][j] = *(const u32x4*)(R + (size_t)rw * DM + c); oo[k][j] = *(const u32x4*)(Y + (size_t)(rw - yoff) * DM + c); } }
;     ...
;         for (int k = 0; k < RP; ++k) { const int row = row0 + k * NGW; if (row < row_hi) {
;             const float rs = __builtin_amdgcn_rsqf(ssv[k] * (1.0f / DM) + RMS_EPS); float s = 0.f;
; #pragma unroll
;             for (int j = 0; j < 2; ++j) { const int c = 8 * lane + 512 * j; const u32x4 r = rr[k][j], o = oo[k][j]; const f32x4 ga = gv[j][0], gb = gv[j][1];
;                 f32x4 ya, yb; ya[0] = bflo(r.x) + bflo(o.x) * rs * ga[0]; ya[1] = bfhi(r.x) + bfhi(o.x) * rs * ga[1]; ya[2] = bflo(r.y) + bflo(o.y) * rs * ga[2]; ya[3] = bfhi(r.y) + bfhi(o.y) * rs * ga[3];
;                 yb[0] = bflo(r.z) + bflo(o.z) * rs * gb[0]; yb[1] = bfhi(r.z) + bfhi(o.z) * rs * gb[1]; yb[2] = bflo(r.w) + bflo(o.w) * rs * gb[2]; yb[3] = bfhi(r.w) + bfhi(o.w) * rs * gb[3];
;                 if (wf32) { *(f32x4*)(outf + (size_t)row * DM + c) = ya; *(f32x4*)(outf + (size_t)row * DM + c + 4) = yb; }
;                 s += (ya[0] * ya[0] + ya[1] * ya[1]) + (ya[2] * ya[2] + ya[3] * ya[3]) + (yb[0] * yb[0] + yb[1] * yb[1]) + (yb[2] * yb[2] + yb[3] * yb[3]);
;                 u32x4 w; w.x = pk2(ya[0], ya[1]); w.y = pk2(ya[2], ya[3]); w.z = pk2(yb[0], yb[1]); w.w = pk2(yb[2], yb[3]); *(u32x4*)(R + (size_t)row * DM + c) = w; }
	v_fmamk_f32 v96, v94, 0x3a800000, v244
	v_rsq_f32_e32 v96, v96
	v_add_u32_e32 v23, 0x1000, v23
	v_lshlrev_b32_e32 v106, 16, v86
	v_and_b32_e32 v107, 0xffff0000, v86
	v_lshlrev_b32_e32 v108, 16, v78
	v_and_b32_e32 v109, 0xffff0000, v78
	v_pk_mul_f32 v[106:107], v[96:97], v[106:107] op_sel_hi:[0,1]
	v_pk_fma_f32 v[98:99], v[10:11], v[106:107], v[108:109]
	v_lshlrev_b32_e32 v106, 16, v87
	v_and_b32_e32 v107, 0xffff0000, v87
	v_lshlrev_b32_e32 v108, 16, v79
	v_and_b32_e32 v109, 0xffff0000, v79
	v_pk_mul_f32 v[106:107], v[96:97], v[106:107] op_sel_hi:[0,1]
	v_pk_fma_f32 v[100:101], v[12:13], v[106:107], v[108:109]
	v_lshlrev_b32_e32 v106, 16, v88
	v_and_b32_e32 v107, 0xffff0000, v88
	v_lshlrev_b32_e32 v108, 16, v80
	v_and_b32_e32 v109, 0xffff0000, v80
	v_pk_mul_f32 v[106:107], v[96:97], v[106:107] op_sel_hi:[0,1]
	v_pk_fma_f32 v[102:103], v[14:15], v[106:107], v[108:109]
	v_lshlrev_b32_e32 v106, 16, v89
	v_and_b32_e32 v107, 0xffff0000, v89
	v_lshlrev_b32_e32 v108, 16, v81
	v_and_b32_e32 v109, 0xffff0000, v81
	v_pk_mul_f32 v[106:107], v[96:97], v[106:107] op_sel_hi:[0,1]
	v_pk_fma_f32 v[104:105], v[16:17], v[106:107], v[108:109]
	global_store_dwordx4 v23, v[98:101], s[6:7]
	global_store_dwordx4 v23, v[102:105], s[6:7] offset:16
	v_lshlrev_b32_e32 v106, 16, v90
	v_and_b32_e32 v107, 0xffff0000, v90
	v_lshlrev_b32_e32 v108, 16, v82
	v_and_b32_e32 v109, 0xffff0000, v82
	v_pk_mul_f32 v[106:107], v[96:97], v[106:107] op_sel_hi:[0,1]
	v_pk_fma_f32 v[98:99], v[2:3], v[106:107], v[108:109]
	v_lshlrev_b32_e32 v106, 16, v91
	v_and_b32_e32 v107, 0xffff0000, v91
	v_lshlrev_b32_e32 v108, 16, v83
	v_and_b32_e32 v109, 0xffff0000, v83
	v_pk_mul_f32 v[106:107], v[96:97], v[106:107] op_sel_hi:[0,1]
	v_pk_fma_f32 v[100:101], v[4:5], v[106:107], v[108:109]
	v_lshlrev_b32_e32 v106, 16, v92
	v_and_b32_e32 v107, 0xffff0000, v92
	v_lshlrev_b32_e32 v108, 16, v84
	v_and_b32_e32 v109, 0xffff0000, v84
	v_pk_mul_f32 v[106:107], v[96:97], v[106:107] op_sel_hi:[0,1]
	v_pk_fma_f32 v[102:103], v[6:7], v[106:107], v[108:109]
	v_lshlrev_b32_e32 v106, 16, v93
	v_and_b32_e32 v107, 0xffff0000, v93
	v_lshlrev_b32_e32 v108, 16, v85
	v_and_b32_e32 v109, 0xffff0000, v85
	v_pk_mul_f32 v[106:107], v[96:97], v[106:107] op_sel_hi:[0,1]
	v_pk_fma_f32 v[104:105], v[8:9], v[106:107], v[108:109]
	global_store_dwordx4 v23, v[98:101], s[6:7] offset:2048
	global_store_dwordx4 v23, v[102:105], s[6:7] offset:2064
	v_add_u32_e32 v18, 0x400000, v18
	v_add_u32_e32 v20, 0x400000, v20
	v_add_u32_e32 v21, 0x2000, v21
	global_load_dwordx4 v[78:81], v18, s[4:5]
	global_load_dwordx4 v[86:89], v20, s[4:5]
	global_load_dwordx4 v[82:85], v18, s[4:5] offset:1024
	global_load_dwordx4 v[90:93], v20, s[4:5] offset:1024
	global_load_dword v94, v21, s[4:5]
	s_waitcnt vmcnt(27)
	v_fmamk_f32 v96, v40, 0x3a800000, v244
	v_rsq_f32_e32 v96, v96
	v_add_u32_e32 v23, 0xf8fff000, v23
	s_lshl_b32 s18, s13, 12
	v_subrev_u32_e32 v23, s18, v23
	v_lshlrev_b32_e32 v106, 16, v32
	v_and_b32_e32 v107, 0xffff0000, v32
	v_lshlrev_b32_e32 v108, 16, v24
	v_and_b32_e32 v109, 0xffff0000, v24
	v_pk_mul_f32 v[106:107], v[96:97], v[106:107] op_sel_hi:[0,1]
	v_pk_fma_f32 v[98:99], v[10:11], v[106:107], v[108:109]
	v_lshlrev_b32_e32 v106, 16, v33
	v_and_b32_e32 v107, 0xffff0000, v33
	v_lshlrev_b32_e32 v108, 16, v25
	v_and_b32_e32 v109, 0xffff0000, v25
	v_pk_mul_f32 v[106:107], v[96:97], v[106:107] op_sel_hi:[0,1]
	v_pk_fma_f32 v[100:101], v[12:13], v[106:107], v[108:109]
	v_lshlrev_b32_e32 v106, 16, v34
	v_and_b32_e32 v107, 0xffff0000, v34
	v_lshlrev_b32_e32 v108, 16, v26
	v_and_b32_e32 v109, 0xffff0000, v26
	v_pk_mul_f32 v[106:107], v[96:97], v[106:107] op_sel_hi:[0,1]
	v_pk_fma_f32 v[102:103], v[14:15], v[106:107], v[108:109]
	v_lshlrev_b32_e32 v106, 16, v35
	v_and_b32_e32 v107, 0xffff0000, v35
	v_lshlrev_b32_e32 v108, 16, v27
	v_and_b32_e32 v109, 0xffff0000, v27
	v_pk_mul_f32 v[106:107], v[96:97], v[106:107] op_sel_hi:[0,1]
	v_pk_fma_f32 v[104:105], v[16:17], v[106:107], v[108:109]
	global_store_dwordx4 v23, v[98:101], s[6:7]
	global_store_dwordx4 v23, v[102:105], s[6:7] offset:16
	v_lshlrev_b32_e32 v106, 16, v36
	v_and_b32_e32 v107, 0xffff0000, v36
	v_lshlrev_b32_e32 v108, 16, v28
	v_and_b32_e32 v109, 0xffff0000, v28
	v_pk_mul_f32 v[106:107], v[96:97], v[106:107] op_sel_hi:[0,1]
	v_pk_fma_f32 v[98:99], v[2:3], v[106:107], v[108:109]
	v_lshlrev_b32_e32 v106, 16, v37
	v_and_b32_e32 v107, 0xffff0000, v37
	v_lshlrev_b32_e32 v108, 16, v29
	v_and_b32_e32 v109, 0xffff0000, v29
	v_pk_mul_f32 v[106:107], v[96:97], v[106:107] op_sel_hi:[0,1]
	v_pk_fma_f32 v[100:101], v[4:5], v[106:107], v[108:109]
	v_lshlrev_b32_e32 v106, 16, v38
	v_and_b32_e32 v107, 0xffff0000, v38
	v_lshlrev_b32_e32 v108, 16, v30
	v_and_b32_e32 v109, 0xffff0000, v30
	v_pk_mul_f32 v[106:107], v[96:97], v[106:107] op_sel_hi:[0,1]
	v_pk_fma_f32 v[102:103], v[6:7], v[106:107], v[108:109]
	v_lshlrev_b32_e32 v106, 16, v39
	v_and_b32_e32 v107, 0xffff0000, v39
	v_lshlrev_b32_e32 v108, 16, v31
	v_and_b32_e32 v109, 0xffff0000, v31
	v_pk_mul_f32 v[106:107], v[96:97], v[106:107] op_sel_hi:[0,1]
	v_pk_fma_f32 v[104:105], v[8:9], v[106:107], v[108:109]
	global_store_dwordx4 v23, v[98:101], s[6:7] offset:2048
	global_store_dwordx4 v23, v[102:105], s[6:7] offset:2064
	v_add_u32_e32 v18, 0x400000, v18
	v_add_u32_e32 v20, 0x400000, v20
	v_add_u32_e32 v21, 0x2000, v21
	global_load_dwordx4 v[24:27], v18, s[4:5]
	global_load_dwordx4 v[32:35], v20, s[4:5]
	global_load_dwordx4 v[28:31], v18, s[4:5] offset:1024
	global_load_dwordx4 v[36:39], v20, s[4:5] offset:1024
	global_load_dword v40, v21, s[4:5]
	s_waitcnt vmcnt(27)
; __device__ __forceinline__ float bflo(unsigned w) { return __uint_as_float(w << 16); }
; __device__ __forceinline__ float bfhi(unsigned w) { return __uint_as_float(w & 0xffff0000u); }
; __device__ __forceinline__ void resid_rows(bf16_t* R, const bf16_t* Y, const float* ssqY, const float* g, float* rstd_out, float* outf, bool wf32, int row_lo, int row_hi, int yoff, int gw, int NGW, int lane) {
;     ...
;         for (int k = 0; k < RP; ++k) { const int row = row0 + k * NGW; const bool ok = row < row_hi; const int rw = ok ? row : row0;
;             ssv[k] = ssqY[rw];
; #pragma unroll
;             for (int j = 0; j < 2; ++j) { const int c = 8 * lane + 512 * j; rr[k][j] = *(const u32x4*)(R + (size_t)rw * DM + c); oo[k][j] = *(const u32x4*)(Y + (size_t)(rw - yoff) * DM + c); } }
;     ...
;         for (int k = 0; k < RP; ++k) { const int row = row0 + k * NGW; if (row < row_hi) {
;             const float rs = __builtin_amdgcn_rsqf(ssv[k] * (1.0f / DM) + RMS_EPS); float s = 0.f;
; #pragma unroll
;             for (int j = 0; j < 2; ++j) { const int c = 8 * lane + 512 * j; const u32x4 r = rr[k][j], o = oo[k][j]; const f32x4 ga = gv[j][0], gb = gv[j][1];
;                 f32x4 ya, yb; ya[0] = bflo(r.x) + bflo(o.x) * rs * ga[0]; ya[1] = bfhi(r.x) + bfhi(o.x) * rs * ga[1]; ya[2] = bflo(r.y) + bflo(o.y) * rs * ga[2]; ya[3] = bfhi(r.y) + bfhi(o.y) * rs * ga[3];
;                 yb[0] = bflo(r.z) + bflo(o.z) * rs * gb[0]; yb[1] = bfhi(r.z) + bfhi(o.z) * rs * gb[1]; yb[2] = bflo(r.w) + bflo(o.w) * rs * gb[2]; yb[3] = bfhi(r.w) + bfhi(o.w) * rs * gb[3];
;                 if (wf32) { *(f32x4*)(outf + (size_t)row * DM + c) = ya; *(f32x4*)(outf + (size_t)row * DM + c + 4) = yb; }
;                 s += (ya[0] * ya[0] + ya[1] * ya[1]) + (ya[2] * ya[2] + ya[3] * ya[3]) + (yb[0] * yb[0] + yb[1] * yb[1]) + (yb[2] * yb[2] + yb[3] * yb[3]);
;                 u32x4 w; w.x = pk2(ya[0], ya[1]); w.y = pk2(ya[2], ya[3]); w.z = pk2(yb[0], yb[1]); w.w = pk2(yb[2], yb[3]); *(u32x4*)(R + (size_t)row * DM + c) = w; }
	v_fmamk_f32 v96, v58, 0x3a800000, v244
	v_rsq_f32_e32 v96, v96
	v_add_u32_e32 v23, 0x800000, v23
	v_lshlrev_b32_e32 v106, 16, v50
	v_and_b32_e32 v107, 0xffff0000, v50
	v_lshlrev_b32_e32 v108, 16, v42
	v_and_b32_e32 v109, 0xffff0000, v42
	v_pk_mul_f32 v[106:107], v[96:97], v[106:107] op_sel_hi:[0,1]
	v_pk_fma_f32 v[98:99], v[10:11], v[106:107], v[108:109]
	v_lshlrev_b32_e32 v106, 16, v51
	v_and_b32_e32 v107, 0xffff0000, v51
	v_lshlrev_b32_e32 v108, 16, v43
	v_and_b32_e32 v109, 0xffff0000, v43
	v_pk_mul_f32 v[106:107], v[96:97], v[106:107] op_sel_hi:[0,1]
	v_pk_fma_f32 v[100:101], v[12:13], v[106:107], v[108:109]
	v_lshlrev_b32_e32 v106, 16, v52
	v_and_b32_e32 v107, 0xffff0000, v52
	v_lshlrev_b32_e32 v108, 16, v44
	v_and_b32_e32 v109, 0xffff0000, v44
	v_pk_mul_f32 v[106:107], v[96:97], v[106:107] op_sel_hi:[0,1]
	v_pk_fma_f32 v[102:103], v[14:15], v[106:107], v[108:109]
	v_lshlrev_b32_e32 v106, 16, v53
	v_and_b32_e32 v107, 0xffff0000, v53
	v_lshlrev_b32_e32 v108, 16, v45
	v_and_b32_e32 v109, 0xffff0000, v45
	v_pk_mul_f32 v[106:107], v[96:97], v[106:107] op_sel_hi:[0,1]
	v_pk_fma_f32 v[104:105], v[16:17], v[106:107], v[108:109]
	global_store_dwordx4 v23, v[98:101], s[6:7]
	global_store_dwordx4 v23, v[102:105], s[6:7] offset:16
	v_lshlrev_b32_e32 v106, 16, v54
	v_and_b32_e32 v107, 0xffff0000, v54
	v_lshlrev_b32_e32 v108, 16, v46
	v_and_b32_e32 v109, 0xffff0000, v46
	v_pk_mul_f32 v[106:107], v[96:97], v[106:107] op_sel_hi:[0,1]
	v_pk_fma_f32 v[98:99], v[2:3], v[106:107], v[108:109]
	v_lshlrev_b32_e32 v106, 16, v55
	v_and_b32_e32 v107, 0xffff0000, v55
	v_lshlrev_b32_e32 v108, 16, v47
	v_and_b32_e32 v109, 0xffff0000, v47
	v_pk_mul_f32 v[106:107], v[96:97], v[106:107] op_sel_hi:[0,1]
	v_pk_fma_f32 v[100:101], v[4:5], v[106:107], v[108:109]
	v_lshlrev_b32_e32 v106, 16, v56
	v_and_b32_e32 v107, 0xffff0000, v56
	v_lshlrev_b32_e32 v108, 16, v48
	v_and_b32_e32 v109, 0xffff0000, v48
	v_pk_mul_f32 v[106:107], v[96:97], v[106:107] op_sel_hi:[0,1]
	v_pk_fma_f32 v[102:103], v[6:7], v[106:107], v[108:109]
	v_lshlrev_b32_e32 v106, 16, v57
	v_and_b32_e32 v107, 0xffff0000, v57
	v_lshlrev_b32_e32 v108, 16, v49
	v_and_b32_e32 v109, 0xffff0000, v49
	v_pk_mul_f32 v[106:107], v[96:97], v[106:107] op_sel_hi:[0,1]
	v_pk_fma_f32 v[104:105], v[8:9], v[106:107], v[108:109]
	global_store_dwordx4 v23, v[98:101], s[6:7] offset:2048
	global_store_dwordx4 v23, v[102:105], s[6:7] offset:2064
	v_add_u32_e32 v18, 0x400000, v18
	v_add_u32_e32 v20, 0x400000, v20
	v_add_u32_e32 v21, 0x2000, v21
	global_load_dwordx4 v[42:45], v18, s[4:5]
	global_load_dwordx4 v[50:53], v20, s[4:5]
	global_load_dwordx4 v[46:49], v18, s[4:5] offset:1024
	global_load_dwordx4 v[54:57], v20, s[4:5] offset:1024
	global_load_dword v58, v21, s[4:5]
	s_waitcnt vmcnt(27)
	v_fmamk_f32 v96, v76, 0x3a800000, v244
	v_rsq_f32_e32 v96, v96
	v_add_u32_e32 v23, 0x800000, v23
	v_lshlrev_b32_e32 v106, 16, v68
	v_and_b32_e32 v107, 0xffff0000, v68
	v_lshlrev_b32_e32 v108, 16, v60
	v_and_b32_e32 v109, 0xffff0000, v60
	v_pk_mul_f32 v[106:107], v[96:97], v[106:107] op_sel_hi:[0,1]
	v_pk_fma_f32 v[98:99], v[10:11], v[106:107], v[108:109]
	v_lshlrev_b32_e32 v106, 16, v69
	v_and_b32_e32 v107, 0xffff0000, v69
	v_lshlrev_b32_e32 v108, 16, v61
	v_and_b32_e32 v109, 0xffff0000, v61
	v_pk_mul_f32 v[106:107], v[96:97], v[106:107] op_sel_hi:[0,1]
	v_pk_fma_f32 v[100:101], v[12:13], v[106:107], v[108:109]
	v_lshlrev_b32_e32 v106, 16, v70
	v_and_b32_e32 v107, 0xffff0000, v70
	v_lshlrev_b32_e32 v108, 16, v62
	v_and_b32_e32 v109, 0xffff0000, v62
	v_pk_mul_f32 v[106:107], v[96:97], v[106:107] op_sel_hi:[0,1]
	v_pk_fma_f32 v[102:103], v[14:15], v[106:107], v[108:109]
	v_lshlrev_b32_e32 v106, 16, v71
	v_and_b32_e32 v107, 0xffff0000, v71
	v_lshlrev_b32_e32 v108, 16, v63
	v_and_b32_e32 v109, 0xffff0000, v63
	v_pk_mul_f32 v[106:107], v[96:97], v[106:107] op_sel_hi:[0,1]
	v_pk_fma_f32 v[104:105], v[16:17], v[106:107], v[108:109]
	global_store_dwordx4 v23, v[98:101], s[6:7]
	global_store_dwordx4 v23, v[102:105], s[6:7] offset:16
	v_lshlrev_b32_e32 v106, 16, v72
	v_and_b32_e32 v107, 0xffff0000, v72
	v_lshlrev_b32_e32 v108, 16, v64
	v_and_b32_e32 v109, 0xffff0000, v64
	v_pk_mul_f32 v[106:107], v[96:97], v[106:107] op_sel_hi:[0,1]
	v_pk_fma_f32 v[98:99], v[2:3], v[106:107], v[108:109]
	v_lshlrev_b32_e32 v106, 16, v73
	v_and_b32_e32 v107, 0xffff0000, v73
	v_lshlrev_b32_e32 v108, 16, v65
	v_and_b32_e32 v109, 0xffff0000, v65
	v_pk_mul_f32 v[106:107], v[96:97], v[106:107] op_sel_hi:[0,1]
	v_pk_fma_f32 v[100:101], v[4:5], v[106:107], v[108:109]
	v_lshlrev_b32_e32 v106, 16, v74
	v_and_b32_e32 v107, 0xffff0000, v74
	v_lshlrev_b32_e32 v108, 16, v66
	v_and_b32_e32 v109, 0xffff0000, v66
	v_pk_mul_f32 v[106:107], v[96:97], v[106:107] op_sel_hi:[0,1]
	v_pk_fma_f32 v[102:103], v[6:7], v[106:107], v[108:109]
	v_lshlrev_b32_e32 v106, 16, v75
	v_and_b32_e32 v107, 0xffff0000, v75
	v_lshlrev_b32_e32 v108, 16, v67
	v_and_b32_e32 v109, 0xffff0000, v67
	v_pk_mul_f32 v[106:107], v[96:97], v[106:107] op_sel_hi:[0,1]
	v_pk_fma_f32 v[104:105], v[8:9], v[106:107], v[108:109]
	global_store_dwordx4 v23, v[98:101], s[6:7] offset:2048
	global_store_dwordx4 v23, v[102:105], s[6:7] offset:2064
	v_add_u32_e32 v18, 0x400000, v18
	v_add_u32_e32 v20, 0x400000, v20
	v_add_u32_e32 v21, 0x2000, v21
	global_load_dwordx4 v[60:63], v18, s[4:5]
	global_load_dwordx4 v[68:71], v20, s[4:5]
	global_load_dwordx4 v[64:67], v18, s[4:5] offset:1024
	global_load_dwordx4 v[72:75], v20, s[4:5] offset:1024
	global_load_dword v76, v21, s[4:5]
	s_waitcnt vmcnt(27)
; __device__ __forceinline__ float bflo(unsigned w) { return __uint_as_float(w << 16); }
; __device__ __forceinline__ float bfhi(unsigned w) { return __uint_as_float(w & 0xffff0000u); }
; __device__ __forceinline__ void resid_rows(bf16_t* R, const bf16_t* Y, const float* ssqY, const float* g, float* rstd_out, float* outf, bool wf32, int row_lo, int row_hi, int yoff, int gw, int NGW, int lane) {
;     ...
;         for (int k = 0; k < RP; ++k) { const int row = row0 + k * NGW; const bool ok = row < row_hi; const int rw = ok ? row : row0;
;             ssv[k] = ssqY[rw];
; #pragma unroll
;             for (int j = 0; j < 2; ++j) { const int c = 8 * lane + 512 * j; rr[k][j] = *(const u32x4*)(R + (size_t)rw * DM + c); oo[k][j] = *(const u32x4*)(Y + (size_t)(rw - yoff) * DM + c); } }
;     ...
;         for (int k = 0; k < RP; ++k) { const int row = row0 + k * NGW; if (row < row_hi) {
;             const float rs = __builtin_amdgcn_rsqf(ssv[k] * (1.0f / DM) + RMS_EPS); float s = 0.f;
; #pragma unroll
;             for (int j = 0; j < 2; ++j) { const int c = 8 * lane + 512 * j; const u32x4 r = rr[k][j], o = oo[k][j]; const f32x4 ga = gv[j][0], gb = gv[j][1];
;                 f32x4 ya, yb; ya[0] = bflo(r.x) + bflo(o.x) * rs * ga[0]; ya[1] = bfhi(r.x) + bfhi(o.x) * rs * ga[1]; ya[2] = bflo(r.y) + bflo(o.y) * rs * ga[2]; ya[3] = bfhi(r.y) + bfhi(o.y) * rs * ga[3];
;                 yb[0] = bflo(r.z) + bflo(o.z) * rs * gb[0]; yb[1] = bfhi(r.z) + bfhi(o.z) * rs * gb[1]; yb[2] = bflo(r.w) + bflo(o.w) * rs * gb[2]; yb[3] = bfhi(r.w) + bfhi(o.w) * rs * gb[3];
;                 if (wf32) { *(f32x4*)(outf + (size_t)row * DM + c) = ya; *(f32x4*)(outf + (size_t)row * DM + c + 4) = yb; }
;                 s += (ya[0] * ya[0] + ya[1] * ya[1]) + (ya[2] * ya[2] + ya[3] * ya[3]) + (yb[0] * yb[0] + yb[1] * yb[1]) + (yb[2] * yb[2] + yb[3] * yb[3]);
;                 u32x4 w; w.x = pk2(ya[0], ya[1]); w.y = pk2(ya[2], ya[3]); w.z = pk2(yb[0], yb[1]); w.w = pk2(yb[2], yb[3]); *(u32x4*)(R + (size_t)row * DM + c) = w; }
	v_fmamk_f32 v96, v94, 0x3a800000, v244
	v_rsq_f32_e32 v96, v96
	v_add_u32_e32 v23, 0x800000, v23
	v_lshlrev_b32_e32 v106, 16, v86
	v_and_b32_e32 v107, 0xffff0000, v86
	v_lshlrev_b32_e32 v108, 16, v78
	v_and_b32_e32 v109, 0xffff0000, v78
	v_pk_mul_f32 v[106:107], v[96:97], v[106:107] op_sel_hi:[0,1]
	v_pk_fma_f32 v[98:99], v[10:11], v[106:107], v[108:109]
	v_lshlrev_b32_e32 v106, 16, v87
	v_and_b32_e32 v107, 0xffff0000, v87
	v_lshlrev_b32_e32 v108, 16, v79
	v_and_b32_e32 v109, 0xffff0000, v79
	v_pk_mul_f32 v[106:107], v[96:97], v[106:107] op_sel_hi:[0,1]
	v_pk_fma_f32 v[100:101], v[12:13], v[106:107], v[108:109]
	v_lshlrev_b32_e32 v106, 16, v88
	v_and_b32_e32 v107, 0xffff0000, v88
	v_lshlrev_b32_e32 v108, 16, v80
	v_and_b32_e32 v109, 0xffff0000, v80
	v_pk_mul_f32 v[106:107], v[96:97], v[106:107] op_sel_hi:[0,1]
	v_pk_fma_f32 v[102:103], v[14:15], v[106:107], v[108:109]
	v_lshlrev_b32_e32 v106, 16, v89
	v_and_b32_e32 v107, 0xffff0000, v89
	v_lshlrev_b32_e32 v108, 16, v81
	v_and_b32_e32 v109, 0xffff0000, v81
	v_pk_mul_f32 v[106:107], v[96:97], v[106:107] op_sel_hi:[0,1]
	v_pk_fma_f32 v[104:105], v[16:17], v[106:107], v[108:109]
	global_store_dwordx4 v23, v[98:101], s[6:7]
	global_store_dwordx4 v23, v[102:105], s[6:7] offset:16
	v_lshlrev_b32_e32 v106, 16, v90
	v_and_b32_e32 v107, 0xffff0000, v90
	v_lshlrev_b32_e32 v108, 16, v82
	v_and_b32_e32 v109, 0xffff0000, v82
	v_pk_mul_f32 v[106:107], v[96:97], v[106:107] op_sel_hi:[0,1]
	v_pk_fma_f32 v[98:99], v[2:3], v[106:107], v[108:109]
	v_lshlrev_b32_e32 v106, 16, v91
	v_and_b32_e32 v107, 0xffff0000, v91
	v_lshlrev_b32_e32 v108, 16, v83
	v_and_b32_e32 v109, 0xffff0000, v83
	v_pk_mul_f32 v[106:107], v[96:97], v[106:107] op_sel_hi:[0,1]
	v_pk_fma_f32 v[100:101], v[4:5], v[106:107], v[108:109]
	v_lshlrev_b32_e32 v106, 16, v92
	v_and_b32_e32 v107, 0xffff0000, v92
	v_lshlrev_b32_e32 v108, 16, v84
	v_and_b32_e32 v109, 0xffff0000, v84
	v_pk_mul_f32 v[106:107], v[96:97], v[106:107] op_sel_hi:[0,1]
	v_pk_fma_f32 v[102:103], v[6:7], v[106:107], v[108:109]
	v_lshlrev_b32_e32 v106, 16, v93
	v_and_b32_e32 v107, 0xffff0000, v93
	v_lshlrev_b32_e32 v108, 16, v85
	v_and_b32_e32 v109, 0xffff0000, v85
	v_pk_mul_f32 v[106:107], v[96:97], v[106:107] op_sel_hi:[0,1]
	v_pk_fma_f32 v[104:105], v[8:9], v[106:107], v[108:109]
	global_store_dwordx4 v23, v[98:101], s[6:7] offset:2048
	global_store_dwordx4 v23, v[102:105], s[6:7] offset:2064
	v_add_u32_e32 v18, 0x400000, v18
	v_add_u32_e32 v20, 0x400000, v20
	v_add_u32_e32 v21, 0x2000, v21
	global_load_dwordx4 v[78:81], v18, s[4:5]
	global_load_dwordx4 v[86:89], v20, s[4:5]
	global_load_dwordx4 v[82:85], v18, s[4:5] offset:1024
	global_load_dwordx4 v[90:93], v20, s[4:5] offset:1024
	global_load_dword v94, v21, s[4:5]
	s_waitcnt vmcnt(27)
	v_fmamk_f32 v96, v40, 0x3a800000, v244
	v_rsq_f32_e32 v96, v96
	v_add_u32_e32 v23, 0x800000, v23
	v_lshlrev_b32_e32 v106, 16, v32
	v_and_b32_e32 v107, 0xffff0000, v32
	v_lshlrev_b32_e32 v108, 16, v24
	v_and_b32_e32 v109, 0xffff0000, v24
	v_pk_mul_f32 v[106:107], v[96:97], v[106:107] op_sel_hi:[0,1]
	v_pk_fma_f32 v[98:99], v[10:11], v[106:107], v[108:109]
	v_lshlrev_b32_e32 v106, 16, v33
	v_and_b32_e32 v107, 0xffff0000, v33
	v_lshlrev_b32_e32 v108, 16, v25
	v_and_b32_e32 v109, 0xffff0000, v25
	v_pk_mul_f32 v[106:107], v[96:97], v[106:107] op_sel_hi:[0,1]
	v_pk_fma_f32 v[100:101], v[12:13], v[106:107], v[108:109]
	v_lshlrev_b32_e32 v106, 16, v34
	v_and_b32_e32 v107, 0xffff0000, v34
	v_lshlrev_b32_e32 v108, 16, v26
	v_and_b32_e32 v109, 0xffff0000, v26
	v_pk_mul_f32 v[106:107], v[96:97], v[106:107] op_sel_hi:[0,1]
	v_pk_fma_f32 v[102:103], v[14:15], v[106:107], v[108:109]
	v_lshlrev_b32_e32 v106, 16, v35
	v_and_b32_e32 v107, 0xffff0000, v35
	v_lshlrev_b32_e32 v108, 16, v27
	v_and_b32_e32 v109, 0xffff0000, v27
	v_pk_mul_f32 v[106:107], v[96:97], v[106:107] op_sel_hi:[0,1]
	v_pk_fma_f32 v[104:105], v[16:17], v[106:107], v[108:109]
	global_store_dwordx4 v23, v[98:101], s[6:7]
	global_store_dwordx4 v23, v[102:105], s[6:7] offset:16
	v_lshlrev_b32_e32 v106, 16, v36
	v_and_b32_e32 v107, 0xffff0000, v36
	v_lshlrev_b32_e32 v108, 16, v28
	v_and_b32_e32 v109, 0xffff0000, v28
	v_pk_mul_f32 v[106:107], v[96:97], v[106:107] op_sel_hi:[0,1]
	v_pk_fma_f32 v[98:99], v[2:3], v[106:107], v[108:109]
	v_lshlrev_b32_e32 v106, 16, v37
	v_and_b32_e32 v107, 0xffff0000, v37
	v_lshlrev_b32_e32 v108, 16, v29
	v_and_b32_e32 v109, 0xffff0000, v29
	v_pk_mul_f32 v[106:107], v[96:97], v[106:107] op_sel_hi:[0,1]
	v_pk_fma_f32 v[100:101], v[4:5], v[106:107], v[108:109]
	v_lshlrev_b32_e32 v106, 16, v38
	v_and_b32_e32 v107, 0xffff0000, v38
	v_lshlrev_b32_e32 v108, 16, v30
	v_and_b32_e32 v109, 0xffff0000, v30
	v_pk_mul_f32 v[106:107], v[96:97], v[106:107] op_sel_hi:[0,1]
	v_pk_fma_f32 v[102:103], v[6:7], v[106:107], v[108:109]
	v_lshlrev_b32_e32 v106, 16, v39
	v_and_b32_e32 v107, 0xffff0000, v39
	v_lshlrev_b32_e32 v108, 16, v31
	v_and_b32_e32 v109, 0xffff0000, v31
	v_pk_mul_f32 v[106:107], v[96:97], v[106:107] op_sel_hi:[0,1]
	v_pk_fma_f32 v[104:105], v[8:9], v[106:107], v[108:109]
	global_store_dwordx4 v23, v[98:101], s[6:7] offset:2048
	global_store_dwordx4 v23, v[102:105], s[6:7] offset:2064
	s_waitcnt vmcnt(22)
; __device__ __forceinline__ float bflo(unsigned w) { return __uint_as_float(w << 16); }
; __device__ __forceinline__ float bfhi(unsigned w) { return __uint_as_float(w & 0xffff0000u); }
; __device__ __forceinline__ void resid_rows(bf16_t* R, const bf16_t* Y, const float* ssqY, const float* g, float* rstd_out, float* outf, bool wf32, int row_lo, int row_hi, int yoff, int gw, int NGW, int lane) {
;     ...
;         for (int k = 0; k < RP; ++k) { const int row = row0 + k * NGW; if (row < row_hi) {
;             const float rs = __builtin_amdgcn_rsqf(ssv[k] * (1.0f / DM) + RMS_EPS); float s = 0.f;
; #pragma unroll
;             for (int j = 0; j < 2; ++j) { const int c = 8 * lane + 512 * j; const u32x4 r = rr[k][j], o = oo[k][j]; const f32x4 ga = gv[j][0], gb = gv[j][1];
;                 f32x4 ya, yb; ya[0] = bflo(r.x) + bflo(o.x) * rs * ga[0]; ya[1] = bfhi(r.x) + bfhi(o.x) * rs * ga[1]; ya[2] = bflo(r.y) + bflo(o.y) * rs * ga[2]; ya[3] = bfhi(r.y) + bfhi(o.y) * rs * ga[3];
;                 yb[0] = bflo(r.z) + bflo(o.z) * rs * gb[0]; yb[1] = bfhi(r.z) + bfhi(o.z) * rs * gb[1]; yb[2] = bflo(r.w) + bflo(o.w) * rs * gb[2]; yb[3] = bfhi(r.w) + bfhi(o.w) * rs * gb[3];
;                 if (wf32) { *(f32x4*)(outf + (size_t)row * DM + c) = ya; *(f32x4*)(outf + (size_t)row * DM + c + 4) = yb; }
;                 s += (ya[0] * ya[0] + ya[1] * ya[1]) + (ya[2] * ya[2] + ya[3] * ya[3]) + (yb[0] * yb[0] + yb[1] * yb[1]) + (yb[2] * yb[2] + yb[3] * yb[3]);
;                 u32x4 w; w.x = pk2(ya[0], ya[1]); w.y = pk2(ya[2], ya[3]); w.z = pk2(yb[0], yb[1]); w.w = pk2(yb[2], yb[3]); *(u32x4*)(R + (size_t)row * DM + c) = w; }
	v_fmamk_f32 v96, v58, 0x3a800000, v244
	v_rsq_f32_e32 v96, v96
	v_add_u32_e32 v23, 0x800000, v23
	v_lshlrev_b32_e32 v106, 16, v50
	v_and_b32_e32 v107, 0xffff0000, v50
	v_lshlrev_b32_e32 v108, 16, v42
	v_and_b32_e32 v109, 0xffff0000, v42
	v_pk_mul_f32 v[106:107], v[96:97], v[106:107] op_sel_hi:[0,1]
	v_pk_fma_f32 v[98:99], v[10:11], v[106:107], v[108:109]
	v_lshlrev_b32_e32 v106, 16, v51
	v_and_b32_e32 v107, 0xffff0000, v51
	v_lshlrev_b32_e32 v108, 16, v43
	v_and_b32_e32 v109, 0xffff0000, v43
	v_pk_mul_f32 v[106:107], v[96:97], v[106:107] op_sel_hi:[0,1]
	v_pk_fma_f32 v[100:101], v[12:13], v[106:107], v[108:109]
	v_lshlrev_b32_e32 v106, 16, v52
	v_and_b32_e32 v107, 0xffff0000, v52
	v_lshlrev_b32_e32 v108, 16, v44
	v_and_b32_e32 v109, 0xffff0000, v44
	v_pk_mul_f32 v[106:107], v[96:97], v[106:107] op_sel_hi:[0,1]
	v_pk_fma_f32 v[102:103], v[14:15], v[106:107], v[108:109]
	v_lshlrev_b32_e32 v106, 16, v53
	v_and_b32_e32 v107, 0xffff0000, v53
	v_lshlrev_b32_e32 v108, 16, v45
	v_and_b32_e32 v109, 0xffff0000, v45
	v_pk_mul_f32 v[106:107], v[96:97], v[106:107] op_sel_hi:[0,1]
	v_pk_fma_f32 v[104:105], v[16:17], v[106:107], v[108:109]
	global_store_dwordx4 v23, v[98:101], s[6:7]
	global_store_dwordx4 v23, v[102:105], s[6:7] offset:16
	v_lshlrev_b32_e32 v106, 16, v54
	v_and_b32_e32 v107, 0xffff0000, v54
	v_lshlrev_b32_e32 v108, 16, v46
	v_and_b32_e32 v109, 0xffff0000, v46
	v_pk_mul_f32 v[106:107], v[96:97], v[106:107] op_sel_hi:[0,1]
	v_pk_fma_f32 v[98:99], v[2:3], v[106:107], v[108:109]
	v_lshlrev_b32_e32 v106, 16, v55
	v_and_b32_e32 v107, 0xffff0000, v55
	v_lshlrev_b32_e32 v108, 16, v47
	v_and_b32_e32 v109, 0xffff0000, v47
	v_pk_mul_f32 v[106:107], v[96:97], v[106:107] op_sel_hi:[0,1]
	v_pk_fma_f32 v[100:101], v[4:5], v[106:107], v[108:109]
	v_lshlrev_b32_e32 v106, 16, v56
	v_and_b32_e32 v107, 0xffff0000, v56
	v_lshlrev_b32_e32 v108, 16, v48
	v_and_b32_e32 v109, 0xffff0000, v48
	v_pk_mul_f32 v[106:107], v[96:97], v[106:107] op_sel_hi:[0,1]
	v_pk_fma_f32 v[102:103], v[6:7], v[106:107], v[108:109]
	v_lshlrev_b32_e32 v106, 16, v57
	v_and_b32_e32 v107, 0xffff0000, v57
	v_lshlrev_b32_e32 v108, 16, v49
	v_and_b32_e32 v109, 0xffff0000, v49
	v_pk_mul_f32 v[106:107], v[96:97], v[106:107] op_sel_hi:[0,1]
	v_pk_fma_f32 v[104:105], v[8:9], v[106:107], v[108:109]
	global_store_dwordx4 v23, v[98:101], s[6:7] offset:2048
	global_store_dwordx4 v23, v[102:105], s[6:7] offset:2064
	s_waitcnt vmcnt(17)
; #define LAS __attribute__((address_space(3)))
; __device__ __forceinline__ float bflo(unsigned w) { return __uint_as_float(w << 16); }
; __device__ __forceinline__ float bfhi(unsigned w) { return __uint_as_float(w & 0xffff0000u); }
; __device__ __forceinline__ int otid() { int t = threadIdx.x; asm volatile("" : "+v"(t)); return t; }
; __device__ __forceinline__ unsigned xb_xcc_id() { return (unsigned)__builtin_amdgcn_s_getreg((3 << 11) | 20) & 0xFu; }
; __device__ __forceinline__ void resid_rows(bf16_t* R, const bf16_t* Y, const float* ssqY, const float* g, float* rstd_out, float* outf, bool wf32, int row_lo, int row_hi, int yoff, int gw, int NGW, int lane) {
;     ...
;         for (int k = 0; k < RP; ++k) { const int row = row0 + k * NGW; if (row < row_hi) {
;             const float rs = __builtin_amdgcn_rsqf(ssv[k] * (1.0f / DM) + RMS_EPS); float s = 0.f;
; #pragma unroll
;             for (int j = 0; j < 2; ++j) { const int c = 8 * lane + 512 * j; const u32x4 r = rr[k][j], o = oo[k][j]; const f32x4 ga = gv[j][0], gb = gv[j][1];
;                 f32x4 ya, yb; ya[0] = bflo(r.x) + bflo(o.x) * rs * ga[0]; ya[1] = bfhi(r.x) + bfhi(o.x) * rs * ga[1]; ya[2] = bflo(r.y) + bflo(o.y) * rs * ga[2]; ya[3] = bfhi(r.y) + bfhi(o.y) * rs * ga[3];
;                 yb[0] = bflo(r.z) + bflo(o.z) * rs * gb[0]; yb[1] = bfhi(r.z) + bfhi(o.z) * rs * gb[1]; yb[2] = bflo(r.w) + bflo(o.w) * rs * gb[2]; yb[3] = bfhi(r.w) + bfhi(o.w) * rs * gb[3];
;                 if (wf32) { *(f32x4*)(outf + (size_t)row * DM + c) = ya; *(f32x4*)(outf + (size_t)row * DM + c + 4) = yb; }
;                 s += (ya[0] * ya[0] + ya[1] * ya[1]) + (ya[2] * ya[2] + ya[3] * ya[3]) + (yb[0] * yb[0] + yb[1] * yb[1]) + (yb[2] * yb[2] + yb[3] * yb[3]);
;                 u32x4 w; w.x = pk2(ya[0], ya[1]); w.y = pk2(ya[2], ya[3]); w.z = pk2(yb[0], yb[1]); w.w = pk2(yb[2], yb[3]); *(u32x4*)(R + (size_t)row * DM + c) = w; }
; __global__ void __launch_bounds__(512, 2) fwd_megakernel(Params P) {
;     ...
;             if (lastl && (P.ph_hi - P.ph_lo > 1)) { XcdBarrier xb_; xb_.bar = (unsigned*)(ws + OFF_BAR); xb_.x = xb_xcc_id(); xb_.st = (volatile LAS unsigned*)(lds + LDS_BYTES - 16); xcd_barrier(xb_); }
;             { const int lane = otid() & 63, gw = bx * 8 + (otid() >> 6);
;               resid_rows(XB, FH0, ssqF, PIN(I_LNFPOST) + l * DM, rstdA, out, lastl, 0, HALF_TOK, 0, gw, NGW, lane); }
	v_fmamk_f32 v96, v76, 0x3a800000, v244
	v_rsq_f32_e32 v96, v96
	v_add_u32_e32 v23, 0x800000, v23
	v_lshlrev_b32_e32 v106, 16, v68
	v_and_b32_e32 v107, 0xffff0000, v68
	v_lshlrev_b32_e32 v108, 16, v60
	v_and_b32_e32 v109, 0xffff0000, v60
	v_pk_mul_f32 v[106:107], v[96:97], v[106:107] op_sel_hi:[0,1]
	v_pk_fma_f32 v[98:99], v[10:11], v[106:107], v[108:109]
	v_lshlrev_b32_e32 v106, 16, v69
	v_and_b32_e32 v107, 0xffff0000, v69
	v_lshlrev_b32_e32 v108, 16, v61
	v_and_b32_e32 v109, 0xffff0000, v61
	v_pk_mul_f32 v[106:107], v[96:97], v[106:107] op_sel_hi:[0,1]
	v_pk_fma_f32 v[100:101], v[12:13], v[106:107], v[108:109]
	v_lshlrev_b32_e32 v106, 16, v70
	v_and_b32_e32 v107, 0xffff0000, v70
	v_lshlrev_b32_e32 v108, 16, v62
	v_and_b32_e32 v109, 0xffff0000, v62
	v_pk_mul_f32 v[106:107], v[96:97], v[106:107] op_sel_hi:[0,1]
	v_pk_fma_f32 v[102:103], v[14:15], v[106:107], v[108:109]
	v_lshlrev_b32_e32 v106, 16, v71
	v_and_b32_e32 v107, 0xffff0000, v71
	v_lshlrev_b32_e32 v108, 16, v63
	v_and_b32_e32 v109, 0xffff0000, v63
	v_pk_mul_f32 v[106:107], v[96:97], v[106:107] op_sel_hi:[0,1]
	v_pk_fma_f32 v[104:105], v[16:17], v[106:107], v[108:109]
	global_store_dwordx4 v23, v[98:101], s[6:7]
	global_store_dwordx4 v23, v[102:105], s[6:7] offset:16
	v_lshlrev_b32_e32 v106, 16, v72
	v_and_b32_e32 v107, 0xffff0000, v72
	v_lshlrev_b32_e32 v108, 16, v64
	v_and_b32_e32 v109, 0xffff0000, v64
	v_pk_mul_f32 v[106:107], v[96:97], v[106:107] op_sel_hi:[0,1]
	v_pk_fma_f32 v[98:99], v[2:3], v[106:107], v[108:109]
	v_lshlrev_b32_e32 v106, 16, v73
	v_and_b32_e32 v107, 0xffff0000, v73
	v_lshlrev_b32_e32 v108, 16, v65
	v_and_b32_e32 v109, 0xffff0000, v65
	v_pk_mul_f32 v[106:107], v[96:97], v[106:107] op_sel_hi:[0,1]
	v_pk_fma_f32 v[100:101], v[4:5], v[106:107], v[108:109]
	v_lshlrev_b32_e32 v106, 16, v74
	v_and_b32_e32 v107, 0xffff0000, v74
	v_lshlrev_b32_e32 v108, 16, v66
	v_and_b32_e32 v109, 0xffff0000, v66
	v_pk_mul_f32 v[106:107], v[96:97], v[106:107] op_sel_hi:[0,1]
	v_pk_fma_f32 v[102:103], v[6:7], v[106:107], v[108:109]
	v_lshlrev_b32_e32 v106, 16, v75
	v_and_b32_e32 v107, 0xffff0000, v75
	v_lshlrev_b32_e32 v108, 16, v67
	v_and_b32_e32 v109, 0xffff0000, v67
	v_pk_mul_f32 v[106:107], v[96:97], v[106:107] op_sel_hi:[0,1]
	v_pk_fma_f32 v[104:105], v[8:9], v[106:107], v[108:109]
	global_store_dwordx4 v23, v[98:101], s[6:7] offset:2048
	global_store_dwordx4 v23, v[102:105], s[6:7] offset:2064
	s_waitcnt vmcnt(12)
	v_fmamk_f32 v96, v94, 0x3a800000, v244
	v_rsq_f32_e32 v96, v96
	v_add_u32_e32 v23, 0x800000, v23
	v_lshlrev_b32_e32 v106, 16, v86
	v_and_b32_e32 v107, 0xffff0000, v86
	v_lshlrev_b32_e32 v108, 16, v78
	v_and_b32_e32 v109, 0xffff0000, v78
	v_pk_mul_f32 v[106:107], v[96:97], v[106:107] op_sel_hi:[0,1]
	v_pk_fma_f32 v[98:99], v[10:11], v[106:107], v[108:109]
	v_lshlrev_b32_e32 v106, 16, v87
	v_and_b32_e32 v107, 0xffff0000, v87
	v_lshlrev_b32_e32 v108, 16, v79
	v_and_b32_e32 v109, 0xffff0000, v79
	v_pk_mul_f32 v[106:107], v[96:97], v[106:107] op_sel_hi:[0,1]
	v_pk_fma_f32 v[100:101], v[12:13], v[106:107], v[108:109]
	v_lshlrev_b32_e32 v106, 16, v88
	v_and_b32_e32 v107, 0xffff0000, v88
	v_lshlrev_b32_e32 v108, 16, v80
	v_and_b32_e32 v109, 0xffff0000, v80
	v_pk_mul_f32 v[106:107], v[96:97], v[106:107] op_sel_hi:[0,1]
	v_pk_fma_f32 v[102:103], v[14:15], v[106:107], v[108:109]
	v_lshlrev_b32_e32 v106, 16, v89
	v_and_b32_e32 v107, 0xffff0000, v89
	v_lshlrev_b32_e32 v108, 16, v81
	v_and_b32_e32 v109, 0xffff0000, v81
	v_pk_mul_f32 v[106:107], v[96:97], v[106:107] op_sel_hi:[0,1]
	v_pk_fma_f32 v[104:105], v[16:17], v[106:107], v[108:109]
	global_store_dwordx4 v23, v[98:101], s[6:7]
	global_store_dwordx4 v23, v[102:105], s[6:7] offset:16
	v_lshlrev_b32_e32 v106, 16, v90
	v_and_b32_e32 v107, 0xffff0000, v90
	v_lshlrev_b32_e32 v108, 16, v82
	v_and_b32_e32 v109, 0xffff0000, v82
	v_pk_mul_f32 v[106:107], v[96:97], v[106:107] op_sel_hi:[0,1]
	v_pk_fma_f32 v[98:99], v[2:3], v[106:107], v[108:109]
	v_lshlrev_b32_e32 v106, 16, v91
	v_and_b32_e32 v107, 0xffff0000, v91
	v_lshlrev_b32_e32 v108, 16, v83
	v_and_b32_e32 v109, 0xffff0000, v83
	v_pk_mul_f32 v[106:107], v[96:97], v[106:107] op_sel_hi:[0,1]
	v_pk_fma_f32 v[100:101], v[4:5], v[106:107], v[108:109]
	v_lshlrev_b32_e32 v106, 16, v92
	v_and_b32_e32 v107, 0xffff0000, v92
	v_lshlrev_b32_e32 v108, 16, v84
	v_and_b32_e32 v109, 0xffff0000, v84
	v_pk_mul_f32 v[106:107], v[96:97], v[106:107] op_sel_hi:[0,1]
	v_pk_fma_f32 v[102:103], v[6:7], v[106:107], v[108:109]
	v_lshlrev_b32_e32 v106, 16, v93
	v_and_b32_e32 v107, 0xffff0000, v93
	v_lshlrev_b32_e32 v108, 16, v85
	v_and_b32_e32 v109, 0xffff0000, v85
	v_pk_mul_f32 v[106:107], v[96:97], v[106:107] op_sel_hi:[0,1]
	v_pk_fma_f32 v[104:105], v[8:9], v[106:107], v[108:109]
	global_store_dwordx4 v23, v[98:101], s[6:7] offset:2048
	global_store_dwordx4 v23, v[102:105], s[6:7] offset:2064
	s_branch .LBB0_907

; #define LAS __attribute__((address_space(3)))
; __device__ __forceinline__ int otid() { int t = threadIdx.x; asm volatile("" : "+v"(t)); return t; }
; __device__ __forceinline__ unsigned xb_xcc_id() { return (unsigned)__builtin_amdgcn_s_getreg((3 << 11) | 20) & 0xFu; }
; #define PIN(i) karg_ptr(8 * (i))
; __global__ void __launch_bounds__(512, 2) fwd_megakernel(Params P) {
;     ...
;             if (lastl && (P.ph_hi - P.ph_lo > 1)) { XcdBarrier xb_; xb_.bar = (unsigned*)(ws + OFF_BAR); xb_.x = xb_xcc_id(); xb_.st = (volatile LAS unsigned*)(lds + LDS_BYTES - 16); xcd_barrier(xb_); }
;             { const int lane = otid() & 63, gw = bx * 8 + (otid() >> 6);
;               resid_rows(XB, FH0, ssqF, PIN(I_LNFPOST) + l * DM, rstdA, out, lastl, 0, HALF_TOK, 0, gw, NGW, lane); }
.LBB0_877:
	v_mov_b32_e32 v2, v0
	v_mov_b32_e32 v3, v0
	v_readlane_b32 s4, v255, 4
	v_ashrrev_i32_e32 v18, 6, v3
	s_mov_b64 s[6:7], s[0:1]
	v_add_u32_e32 v86, s4, v18
	s_mov_b64 s[4:5], s[0:1]
	s_mov_b64 s[10:11], s[0:1]
	s_mov_b64 s[12:13], s[0:1]
	s_mov_b64 s[8:9], s[0:1]
	v_cmp_gt_i32_e32 vcc, s47, v86
	s_and_saveexec_b64 s[16:17], vcc
	s_cbranch_execz .LBB0_907
	s_branch .LBB0_907
